# attention steady loops unrolled x3: K-ring slot static, K fragment ds_read addresses folded into immediate offsets (8 VALU per step pair removed)
# baseline (speedup 1.0000x reference)
.Lst0_loop:
	s_cmp_lg_u32 s41, 0
	s_cbranch_scc1 .Lst0_single
	s_cmp_lt_u32 s21, 56
	s_cbranch_scc1 .Lst0_u3

.Lst0_u3:
	s_lshl_b32 s46, s41, 14
	s_add_i32 s46, s58, s46
	s_mov_b32 m0, s46
	s_nop 0
	global_load_lds_dwordx4 v198, s[98:99]
	s_add_i32 m0, s46, 0x400
	s_nop 0
	global_load_lds_dwordx4 v194, s[98:99]
	s_add_i32 s48, s20, 0xffffc000
	s_and_b32 s48, s48, 0x8000
	s_add_i32 s48, s58, s48
	s_add_i32 m0, s48, 0xc000
	s_nop 0
	global_load_lds_dwordx4 v196, s[100:101]
	s_add_i32 m0, s48, 0xc400
	s_nop 0
	global_load_lds_dwordx4 v192, s[100:101]
	s_add_i32 s46, s41, 1
	s_cmp_lg_u32 s41, 2
	s_cselect_b32 s41, s46, 0
	s_lshl_b32 s46, s41, 14
	s_add_i32 s49, s46, 0
	s_add_i32 s46, s20, 0xffff4000
	ds_read_b128 v[96:99], v205 offset:16384
	ds_read_b128 v[100:103], v205 offset:24576
	s_waitcnt lgkmcnt(0)
	v_mfma_f32_32x32x16_bf16 v[112:127], v[96:99], v[160:163], 0
	ds_read_b128 v[128:131], v211 offset:16384
	ds_read_b128 v[132:135], v211 offset:24576
	ds_read_b128 v[136:139], v212 offset:16384
	s_and_b32 s46, s46, 0x8000
	s_add_i32 s48, s46, 0
	v_exp_f32_e32 v140, v48
	v_exp_f32_e32 v141, v49
	v_exp_f32_e32 v142, v50
	v_exp_f32_e32 v143, v51
	ds_read_b128 v[48:51], v212 offset:24576
	v_mfma_f32_32x32x16_bf16 v[96:111], v[100:103], v[160:163], 0
	v_exp_f32_e32 v144, v52
	v_exp_f32_e32 v145, v53
	v_exp_f32_e32 v146, v54
	v_exp_f32_e32 v147, v55
	s_waitcnt lgkmcnt(0)
	v_mfma_f32_32x32x16_bf16 v[112:127], v[128:131], v[164:167], v[112:127]
	ds_read_b128 v[52:55], v213 offset:16384
	v_exp_f32_e32 v148, v56
	v_exp_f32_e32 v149, v57
	v_exp_f32_e32 v150, v58
	v_exp_f32_e32 v151, v59
	v_mfma_f32_32x32x16_bf16 v[96:111], v[132:135], v[164:167], v[96:111]
	ds_read_b128 v[56:59], v213 offset:24576
	v_exp_f32_e32 v128, v60
	v_exp_f32_e32 v129, v61
	v_exp_f32_e32 v130, v62
	v_exp_f32_e32 v131, v63
	v_mfma_f32_32x32x16_bf16 v[112:127], v[136:139], v[168:171], v[112:127]
	v_add_u32_e32 v156, s48, v206
	ds_read_b128 v[60:63], v156 offset:49152
	v_exp_f32_e32 v132, v32
	v_exp_f32_e32 v133, v33
	v_exp_f32_e32 v134, v34
	v_exp_f32_e32 v135, v35
	v_mfma_f32_32x32x16_bf16 v[96:111], v[48:51], v[168:171], v[96:111]
	ds_read_b128 v[32:35], v156 offset:53248
	v_exp_f32_e32 v136, v36
	v_exp_f32_e32 v137, v37
	v_exp_f32_e32 v138, v38
	v_exp_f32_e32 v139, v39
	s_waitcnt lgkmcnt(0)
	v_mfma_f32_32x32x16_bf16 v[112:127], v[52:55], v[172:175], v[112:127]
	ds_read_b128 v[36:39], v156 offset:57344
	v_exp_f32_e32 v152, v40
	v_exp_f32_e32 v153, v41
	v_exp_f32_e32 v154, v42
	v_exp_f32_e32 v155, v43
	v_mfma_f32_32x32x16_bf16 v[96:111], v[56:59], v[172:175], v[96:111]
	ds_read_b128 v[40:43], v156 offset:61440
	v_exp_f32_e32 v156, v44
	v_exp_f32_e32 v157, v45
	v_exp_f32_e32 v158, v46
	v_exp_f32_e32 v159, v47
	v_cvt_pk_bf16_f32 v44, v140, v141
	v_cvt_pk_bf16_f32 v45, v142, v143
	v_cvt_pk_bf16_f32 v46, v144, v145
	v_cvt_pk_bf16_f32 v47, v146, v147
	s_nop 1
	v_mfma_f32_32x32x16_bf16 v[80:95], v[60:63], v[44:47], v[80:95]
	v_xad_u32 v178, v206, 32, s48
	ds_read_b128 v[48:51], v178 offset:49152
	v_cvt_pk_bf16_f32 v52, v148, v149
	v_cvt_pk_bf16_f32 v53, v150, v151
	v_cvt_pk_bf16_f32 v54, v128, v129
	v_cvt_pk_bf16_f32 v55, v130, v131
	v_mfma_f32_32x32x16_bf16 v[64:79], v[32:35], v[44:47], v[64:79]
	ds_read_b128 v[56:59], v178 offset:53248
	v_pk_add_f32 v[62:63], v[146:147], v[142:143]
	v_pk_add_f32 v[60:61], v[144:145], v[140:141]
	s_waitcnt lgkmcnt(0)
	v_mfma_f32_32x32x16_bf16 v[16:31], v[36:39], v[44:47], v[16:31]
	ds_read_b128 v[32:35], v178 offset:57344
	v_add_f32_e64 v62, v150, v62
	v_add_f32_e64 v63, v151, v63
	v_add_f32_e64 v60, v148, v60
	v_add_f32_e64 v61, v149, v61
	v_pk_add_f32 v[62:63], v[130:131], v[62:63]
	v_pk_add_f32 v[60:61], v[128:129], v[60:61]
	v_mfma_f32_32x32x16_bf16 v[0:15], v[40:43], v[44:47], v[0:15]
	ds_read_b128 v[36:39], v178 offset:61440
	v_mfma_f32_32x32x16_bf16 v[80:95], v[48:51], v[52:55], v[80:95]
	v_xad_u32 v140, v206, 64, s48
	ds_read_b128 v[40:43], v140 offset:49152
	v_cvt_pk_bf16_f32 v44, v132, v133
	v_cvt_pk_bf16_f32 v45, v134, v135
	v_cvt_pk_bf16_f32 v46, v136, v137
	v_cvt_pk_bf16_f32 v47, v138, v139
	v_mfma_f32_32x32x16_bf16 v[64:79], v[56:59], v[52:55], v[64:79]
	ds_read_b128 v[48:51], v140 offset:53248
	v_add_f32_e64 v62, v134, v62
	v_add_f32_e64 v63, v135, v63
	v_add_f32_e64 v60, v132, v60
	v_add_f32_e64 v61, v133, v61
	v_pk_add_f32 v[62:63], v[138:139], v[62:63]
	v_pk_add_f32 v[60:61], v[136:137], v[60:61]
	s_waitcnt lgkmcnt(0)
	v_mfma_f32_32x32x16_bf16 v[16:31], v[32:35], v[52:55], v[16:31]
	ds_read_b128 v[56:59], v140 offset:57344
	v_add_f32_e64 v62, v154, v62
	v_add_f32_e64 v63, v155, v63
	v_add_f32_e64 v60, v152, v60
	v_add_f32_e64 v61, v153, v61
	v_pk_add_f32 v[130:131], v[158:159], v[62:63]
	v_pk_add_f32 v[128:129], v[156:157], v[60:61]
	v_mfma_f32_32x32x16_bf16 v[0:15], v[36:39], v[52:55], v[0:15]
	ds_read_b128 v[32:35], v140 offset:61440
	v_mfma_f32_32x32x16_bf16 v[80:95], v[40:43], v[44:47], v[80:95]
	v_add_u32_e32 v60, s48, v209
	ds_read_b128 v[36:39], v60 offset:49152
	v_cvt_pk_bf16_f32 v52, v152, v153
	v_cvt_pk_bf16_f32 v53, v154, v155
	v_cvt_pk_bf16_f32 v54, v156, v157
	v_cvt_pk_bf16_f32 v55, v158, v159
	v_mfma_f32_32x32x16_bf16 v[64:79], v[48:51], v[44:47], v[64:79]
	ds_read_b128 v[40:43], v60 offset:53248
	s_waitcnt lgkmcnt(0)
	v_mfma_f32_32x32x16_bf16 v[16:31], v[56:59], v[44:47], v[16:31]
	ds_read_b128 v[48:51], v60 offset:57344
	v_mfma_f32_32x32x16_bf16 v[0:15], v[32:35], v[44:47], v[0:15]
	ds_read_b128 v[56:59], v60 offset:61440
	v_mfma_f32_32x32x16_bf16 v[80:95], v[36:39], v[52:55], v[80:95]
	v_mfma_f32_32x32x16_bf16 v[64:79], v[40:43], v[52:55], v[64:79]
	s_waitcnt lgkmcnt(0)
	v_mfma_f32_32x32x16_bf16 v[16:31], v[48:51], v[52:55], v[16:31]
	v_mfma_f32_32x32x16_bf16 v[0:15], v[56:59], v[52:55], v[0:15]
	s_waitcnt vmcnt(4) lgkmcnt(0)
	s_barrier
	s_add_u32 s68, s98, 0x18000
	s_addc_u32 s69, s99, 0
	s_add_i32 s49, s49, s57
	s_mov_b32 m0, s49
	s_nop 0
	global_load_lds_dwordx4 v198, s[68:69]
	s_add_i32 m0, s49, 0x400
	s_nop 0
	global_load_lds_dwordx4 v194, s[68:69]
	s_add_u32 s44, s100, 0x80
	s_addc_u32 s45, s101, 0
	s_and_b32 s49, s20, 0xc000
	s_add_i32 s49, s58, s49
	s_add_i32 m0, s49, 0xc000
	s_nop 0
	global_load_lds_dwordx4 v196, s[44:45]
	s_add_i32 m0, s49, 0xc400
	s_nop 0
	global_load_lds_dwordx4 v192, s[44:45]
	s_add_i32 s48, s48, 0xc000
	s_add_i32 s44, s41, 1
	s_cmp_lg_u32 s41, 2
	s_cselect_b32 s41, s44, 0
	s_lshl_b32 s44, s41, 14
	s_add_i32 s44, s44, 0
	v_exp_f32_e32 v144, v112
	ds_read_b128 v[32:35], v205 offset:32768
	ds_read_b128 v[36:39], v205 offset:40960
	s_waitcnt lgkmcnt(0)
	v_mfma_f32_32x32x16_bf16 v[48:63], v[32:35], v[160:163], 0
	ds_read_b128 v[132:135], v211 offset:32768
	ds_read_b128 v[136:139], v211 offset:40960
	ds_read_b128 v[140:143], v212 offset:32768
	v_exp_f32_e32 v145, v113
	v_exp_f32_e32 v146, v114
	v_exp_f32_e32 v147, v115
	ds_read_b128 v[112:115], v212 offset:40960
	v_mfma_f32_32x32x16_bf16 v[32:47], v[36:39], v[160:163], 0
	v_exp_f32_e32 v148, v116
	v_exp_f32_e32 v149, v117
	v_exp_f32_e32 v150, v118
	v_exp_f32_e32 v151, v119
	s_waitcnt lgkmcnt(0)
	v_mfma_f32_32x32x16_bf16 v[48:63], v[132:135], v[164:167], v[48:63]
	ds_read_b128 v[116:119], v213 offset:32768
	v_exp_f32_e32 v152, v120
	v_exp_f32_e32 v153, v121
	v_exp_f32_e32 v154, v122
	v_exp_f32_e32 v155, v123
	v_mfma_f32_32x32x16_bf16 v[32:47], v[136:139], v[164:167], v[32:47]
	ds_read_b128 v[120:123], v213 offset:40960
	v_exp_f32_e32 v156, v124
	v_exp_f32_e32 v157, v125
	v_exp_f32_e32 v158, v126
	v_exp_f32_e32 v159, v127
	v_mfma_f32_32x32x16_bf16 v[48:63], v[140:143], v[168:171], v[48:63]
	v_add_u32_e32 v132, s48, v206
	ds_read_b128 v[124:127], v132 offset:16384
	v_exp_f32_e32 v136, v96
	v_exp_f32_e32 v137, v97
	v_exp_f32_e32 v138, v98
	v_exp_f32_e32 v139, v99
	v_mfma_f32_32x32x16_bf16 v[32:47], v[112:115], v[168:171], v[32:47]
	ds_read_b128 v[96:99], v132 offset:20480
	v_exp_f32_e32 v140, v100
	v_exp_f32_e32 v141, v101
	v_exp_f32_e32 v142, v102
	v_exp_f32_e32 v143, v103
	s_waitcnt lgkmcnt(0)
	v_mfma_f32_32x32x16_bf16 v[48:63], v[116:119], v[172:175], v[48:63]
	ds_read_b128 v[100:103], v132 offset:24576
	v_exp_f32_e32 v178, v104
	v_exp_f32_e32 v179, v105
	v_exp_f32_e32 v180, v106
	v_exp_f32_e32 v181, v107
	v_mfma_f32_32x32x16_bf16 v[32:47], v[120:123], v[172:175], v[32:47]
	ds_read_b128 v[104:107], v132 offset:28672
	v_exp_f32_e32 v182, v108
	v_exp_f32_e32 v183, v109
	v_exp_f32_e32 v184, v110
	v_exp_f32_e32 v185, v111
	v_cvt_pk_bf16_f32 v108, v144, v145
	v_cvt_pk_bf16_f32 v109, v146, v147
	v_cvt_pk_bf16_f32 v110, v148, v149
	v_cvt_pk_bf16_f32 v111, v150, v151
	s_nop 1
	v_mfma_f32_32x32x16_bf16 v[80:95], v[124:127], v[108:111], v[80:95]
	v_xad_u32 v186, v206, 32, s48
	ds_read_b128 v[112:115], v186 offset:16384
	v_cvt_pk_bf16_f32 v116, v152, v153
	v_cvt_pk_bf16_f32 v117, v154, v155
	v_cvt_pk_bf16_f32 v118, v156, v157
	v_cvt_pk_bf16_f32 v119, v158, v159
	v_mfma_f32_32x32x16_bf16 v[64:79], v[96:99], v[108:111], v[64:79]
	ds_read_b128 v[120:123], v186 offset:20480
	v_pk_add_f32 v[126:127], v[150:151], v[146:147]
	v_pk_add_f32 v[124:125], v[148:149], v[144:145]
	s_waitcnt lgkmcnt(0)
	v_mfma_f32_32x32x16_bf16 v[16:31], v[100:103], v[108:111], v[16:31]
	ds_read_b128 v[132:135], v186 offset:24576
	v_add_f32_e64 v98, v154, v126
	v_add_f32_e64 v99, v155, v127
	v_add_f32_e64 v96, v152, v124
	v_add_f32_e64 v97, v153, v125
	v_pk_add_f32 v[98:99], v[158:159], v[98:99]
	v_pk_add_f32 v[96:97], v[156:157], v[96:97]
	v_mfma_f32_32x32x16_bf16 v[0:15], v[104:107], v[108:111], v[0:15]
	ds_read_b128 v[100:103], v186 offset:28672
	v_mfma_f32_32x32x16_bf16 v[80:95], v[112:115], v[116:119], v[80:95]
	v_xad_u32 v124, v206, 64, s48
	ds_read_b128 v[104:107], v124 offset:16384
	v_cvt_pk_bf16_f32 v108, v136, v137
	v_cvt_pk_bf16_f32 v109, v138, v139
	v_cvt_pk_bf16_f32 v110, v140, v141
	v_cvt_pk_bf16_f32 v111, v142, v143
	v_mfma_f32_32x32x16_bf16 v[64:79], v[120:123], v[116:119], v[64:79]
	ds_read_b128 v[112:115], v124 offset:20480
	v_add_f32_e64 v98, v138, v98
	v_add_f32_e64 v99, v139, v99
	v_add_f32_e64 v96, v136, v96
	v_add_f32_e64 v97, v137, v97
	v_pk_add_f32 v[98:99], v[142:143], v[98:99]
	v_pk_add_f32 v[96:97], v[140:141], v[96:97]
	s_waitcnt lgkmcnt(0)
	v_mfma_f32_32x32x16_bf16 v[16:31], v[132:135], v[116:119], v[16:31]
	ds_read_b128 v[120:123], v124 offset:24576
	v_add_f32_e64 v98, v180, v98
	v_add_f32_e64 v99, v181, v99
	v_add_f32_e64 v96, v178, v96
	v_add_f32_e64 v97, v179, v97
	v_pk_add_f32 v[98:99], v[184:185], v[98:99]
	v_pk_add_f32 v[96:97], v[182:183], v[96:97]
	v_mfma_f32_32x32x16_bf16 v[0:15], v[100:103], v[116:119], v[0:15]
	ds_read_b128 v[124:127], v124 offset:28672
	v_mfma_f32_32x32x16_bf16 v[80:95], v[104:107], v[108:111], v[80:95]
	v_add_u32_e32 v132, s48, v209
	ds_read_b128 v[100:103], v132 offset:16384
	v_cvt_pk_bf16_f32 v116, v178, v179
	v_cvt_pk_bf16_f32 v117, v180, v181
	v_cvt_pk_bf16_f32 v118, v182, v183
	v_cvt_pk_bf16_f32 v119, v184, v185
	v_mfma_f32_32x32x16_bf16 v[64:79], v[112:115], v[108:111], v[64:79]
	ds_read_b128 v[104:107], v132 offset:20480
	s_waitcnt lgkmcnt(0)
	v_mfma_f32_32x32x16_bf16 v[16:31], v[120:123], v[108:111], v[16:31]
	ds_read_b128 v[112:115], v132 offset:24576
	v_mfma_f32_32x32x16_bf16 v[0:15], v[124:127], v[108:111], v[0:15]
	ds_read_b128 v[120:123], v132 offset:28672
	v_mfma_f32_32x32x16_bf16 v[80:95], v[100:103], v[116:119], v[80:95]
	v_mfma_f32_32x32x16_bf16 v[64:79], v[104:107], v[116:119], v[64:79]
	s_waitcnt lgkmcnt(0)
	v_mfma_f32_32x32x16_bf16 v[16:31], v[112:115], v[116:119], v[16:31]
	v_mfma_f32_32x32x16_bf16 v[0:15], v[120:123], v[116:119], v[0:15]
	s_waitcnt vmcnt(4) lgkmcnt(0)
	v_add_f32_e32 v100, v128, v129
	v_add_f32_e32 v101, v130, v131
	v_add_f32_e32 v100, v100, v101
	v_add_f32_e32 v96, v96, v97
	v_add_f32_e32 v97, v98, v99
	s_barrier
	v_add_f32_e32 v100, v177, v100
	v_add_f32_e32 v96, v96, v97
	v_add_f32_e32 v177, v100, v96
	s_add_i32 s21, s21, 2
	s_addk_i32 s15, 0x80
	s_add_i32 s20, s20, 0x8000
	s_add_u32 s98, s98, 0x30000
	s_addc_u32 s99, s99, 0
	s_add_u32 s100, s100, 0x100
	s_addc_u32 s101, s101, 0
	s_lshl_b32 s46, s41, 14
	s_add_i32 s46, s58, s46
	s_mov_b32 m0, s46
	s_nop 0
	global_load_lds_dwordx4 v198, s[98:99]
	s_add_i32 m0, s46, 0x400
	s_nop 0
	global_load_lds_dwordx4 v194, s[98:99]
	s_add_i32 s48, s20, 0xffffc000
	s_and_b32 s48, s48, 0x8000
	s_add_i32 s48, s58, s48
	s_add_i32 m0, s48, 0xc000
	s_nop 0
	global_load_lds_dwordx4 v196, s[100:101]
	s_add_i32 m0, s48, 0xc400
	s_nop 0
	global_load_lds_dwordx4 v192, s[100:101]
	s_add_i32 s46, s41, 1
	s_cmp_lg_u32 s41, 2
	s_cselect_b32 s41, s46, 0
	s_lshl_b32 s46, s41, 14
	s_add_i32 s49, s46, 0
	s_add_i32 s46, s20, 0xffff4000
	ds_read_b128 v[96:99], v205
	ds_read_b128 v[100:103], v205 offset:8192
	s_waitcnt lgkmcnt(0)
	v_mfma_f32_32x32x16_bf16 v[112:127], v[96:99], v[160:163], 0
	ds_read_b128 v[128:131], v211
	ds_read_b128 v[132:135], v211 offset:8192
	ds_read_b128 v[136:139], v212
	s_and_b32 s46, s46, 0x8000
	s_add_i32 s48, s46, 0
	v_exp_f32_e32 v140, v48
	v_exp_f32_e32 v141, v49
	v_exp_f32_e32 v142, v50
	v_exp_f32_e32 v143, v51
	ds_read_b128 v[48:51], v212 offset:8192
	v_mfma_f32_32x32x16_bf16 v[96:111], v[100:103], v[160:163], 0
	v_exp_f32_e32 v144, v52
	v_exp_f32_e32 v145, v53
	v_exp_f32_e32 v146, v54
	v_exp_f32_e32 v147, v55
	s_waitcnt lgkmcnt(0)
	v_mfma_f32_32x32x16_bf16 v[112:127], v[128:131], v[164:167], v[112:127]
	ds_read_b128 v[52:55], v213
	v_exp_f32_e32 v148, v56
	v_exp_f32_e32 v149, v57
	v_exp_f32_e32 v150, v58
	v_exp_f32_e32 v151, v59
	v_mfma_f32_32x32x16_bf16 v[96:111], v[132:135], v[164:167], v[96:111]
	ds_read_b128 v[56:59], v213 offset:8192
	v_exp_f32_e32 v128, v60
	v_exp_f32_e32 v129, v61
	v_exp_f32_e32 v130, v62
	v_exp_f32_e32 v131, v63
	v_mfma_f32_32x32x16_bf16 v[112:127], v[136:139], v[168:171], v[112:127]
	v_add_u32_e32 v156, s48, v206
	ds_read_b128 v[60:63], v156 offset:49152
	v_exp_f32_e32 v132, v32
	v_exp_f32_e32 v133, v33
	v_exp_f32_e32 v134, v34
	v_exp_f32_e32 v135, v35
	v_mfma_f32_32x32x16_bf16 v[96:111], v[48:51], v[168:171], v[96:111]
	ds_read_b128 v[32:35], v156 offset:53248
	v_exp_f32_e32 v136, v36
	v_exp_f32_e32 v137, v37
	v_exp_f32_e32 v138, v38
	v_exp_f32_e32 v139, v39
	s_waitcnt lgkmcnt(0)
	v_mfma_f32_32x32x16_bf16 v[112:127], v[52:55], v[172:175], v[112:127]
	ds_read_b128 v[36:39], v156 offset:57344
	v_exp_f32_e32 v152, v40
	v_exp_f32_e32 v153, v41
	v_exp_f32_e32 v154, v42
	v_exp_f32_e32 v155, v43
	v_mfma_f32_32x32x16_bf16 v[96:111], v[56:59], v[172:175], v[96:111]
	ds_read_b128 v[40:43], v156 offset:61440
	v_exp_f32_e32 v156, v44
	v_exp_f32_e32 v157, v45
	v_exp_f32_e32 v158, v46
	v_exp_f32_e32 v159, v47
	v_cvt_pk_bf16_f32 v44, v140, v141
	v_cvt_pk_bf16_f32 v45, v142, v143
	v_cvt_pk_bf16_f32 v46, v144, v145
	v_cvt_pk_bf16_f32 v47, v146, v147
	s_nop 1
	v_mfma_f32_32x32x16_bf16 v[80:95], v[60:63], v[44:47], v[80:95]
	v_xad_u32 v178, v206, 32, s48
	ds_read_b128 v[48:51], v178 offset:49152
	v_cvt_pk_bf16_f32 v52, v148, v149
	v_cvt_pk_bf16_f32 v53, v150, v151
	v_cvt_pk_bf16_f32 v54, v128, v129
	v_cvt_pk_bf16_f32 v55, v130, v131
	v_mfma_f32_32x32x16_bf16 v[64:79], v[32:35], v[44:47], v[64:79]
	ds_read_b128 v[56:59], v178 offset:53248
	v_pk_add_f32 v[62:63], v[146:147], v[142:143]
	v_pk_add_f32 v[60:61], v[144:145], v[140:141]
	s_waitcnt lgkmcnt(0)
	v_mfma_f32_32x32x16_bf16 v[16:31], v[36:39], v[44:47], v[16:31]
	ds_read_b128 v[32:35], v178 offset:57344
	v_add_f32_e64 v62, v150, v62
	v_add_f32_e64 v63, v151, v63
	v_add_f32_e64 v60, v148, v60
	v_add_f32_e64 v61, v149, v61
	v_pk_add_f32 v[62:63], v[130:131], v[62:63]
	v_pk_add_f32 v[60:61], v[128:129], v[60:61]
	v_mfma_f32_32x32x16_bf16 v[0:15], v[40:43], v[44:47], v[0:15]
	ds_read_b128 v[36:39], v178 offset:61440
	v_mfma_f32_32x32x16_bf16 v[80:95], v[48:51], v[52:55], v[80:95]
	v_xad_u32 v140, v206, 64, s48
	ds_read_b128 v[40:43], v140 offset:49152
	v_cvt_pk_bf16_f32 v44, v132, v133
	v_cvt_pk_bf16_f32 v45, v134, v135
	v_cvt_pk_bf16_f32 v46, v136, v137
	v_cvt_pk_bf16_f32 v47, v138, v139
	v_mfma_f32_32x32x16_bf16 v[64:79], v[56:59], v[52:55], v[64:79]
	ds_read_b128 v[48:51], v140 offset:53248
	v_add_f32_e64 v62, v134, v62
	v_add_f32_e64 v63, v135, v63
	v_add_f32_e64 v60, v132, v60
	v_add_f32_e64 v61, v133, v61
	v_pk_add_f32 v[62:63], v[138:139], v[62:63]
	v_pk_add_f32 v[60:61], v[136:137], v[60:61]
	s_waitcnt lgkmcnt(0)
	v_mfma_f32_32x32x16_bf16 v[16:31], v[32:35], v[52:55], v[16:31]
	ds_read_b128 v[56:59], v140 offset:57344
	v_add_f32_e64 v62, v154, v62
	v_add_f32_e64 v63, v155, v63
	v_add_f32_e64 v60, v152, v60
	v_add_f32_e64 v61, v153, v61
	v_pk_add_f32 v[130:131], v[158:159], v[62:63]
	v_pk_add_f32 v[128:129], v[156:157], v[60:61]
	v_mfma_f32_32x32x16_bf16 v[0:15], v[36:39], v[52:55], v[0:15]
	ds_read_b128 v[32:35], v140 offset:61440
	v_mfma_f32_32x32x16_bf16 v[80:95], v[40:43], v[44:47], v[80:95]
	v_add_u32_e32 v60, s48, v209
	ds_read_b128 v[36:39], v60 offset:49152
	v_cvt_pk_bf16_f32 v52, v152, v153
	v_cvt_pk_bf16_f32 v53, v154, v155
	v_cvt_pk_bf16_f32 v54, v156, v157
	v_cvt_pk_bf16_f32 v55, v158, v159
	v_mfma_f32_32x32x16_bf16 v[64:79], v[48:51], v[44:47], v[64:79]
	ds_read_b128 v[40:43], v60 offset:53248
	s_waitcnt lgkmcnt(0)
	v_mfma_f32_32x32x16_bf16 v[16:31], v[56:59], v[44:47], v[16:31]
	ds_read_b128 v[48:51], v60 offset:57344
	v_mfma_f32_32x32x16_bf16 v[0:15], v[32:35], v[44:47], v[0:15]
	ds_read_b128 v[56:59], v60 offset:61440
	v_mfma_f32_32x32x16_bf16 v[80:95], v[36:39], v[52:55], v[80:95]
	v_mfma_f32_32x32x16_bf16 v[64:79], v[40:43], v[52:55], v[64:79]
	s_waitcnt lgkmcnt(0)
	v_mfma_f32_32x32x16_bf16 v[16:31], v[48:51], v[52:55], v[16:31]
	v_mfma_f32_32x32x16_bf16 v[0:15], v[56:59], v[52:55], v[0:15]
	s_waitcnt vmcnt(4) lgkmcnt(0)
	s_barrier
	s_add_u32 s68, s98, 0x18000
	s_addc_u32 s69, s99, 0
	s_add_i32 s49, s49, s57
	s_mov_b32 m0, s49
	s_nop 0
	global_load_lds_dwordx4 v198, s[68:69]
	s_add_i32 m0, s49, 0x400
	s_nop 0
	global_load_lds_dwordx4 v194, s[68:69]
	s_add_u32 s44, s100, 0x80
	s_addc_u32 s45, s101, 0
	s_and_b32 s49, s20, 0xc000
	s_add_i32 s49, s58, s49
	s_add_i32 m0, s49, 0xc000
	s_nop 0
	global_load_lds_dwordx4 v196, s[44:45]
	s_add_i32 m0, s49, 0xc400
	s_nop 0
	global_load_lds_dwordx4 v192, s[44:45]
	s_add_i32 s48, s48, 0xc000
	s_add_i32 s44, s41, 1
	s_cmp_lg_u32 s41, 2
	s_cselect_b32 s41, s44, 0
	s_lshl_b32 s44, s41, 14
	s_add_i32 s44, s44, 0
	v_exp_f32_e32 v144, v112
	ds_read_b128 v[32:35], v205 offset:16384
	ds_read_b128 v[36:39], v205 offset:24576
	s_waitcnt lgkmcnt(0)
	v_mfma_f32_32x32x16_bf16 v[48:63], v[32:35], v[160:163], 0
	ds_read_b128 v[132:135], v211 offset:16384
	ds_read_b128 v[136:139], v211 offset:24576
	ds_read_b128 v[140:143], v212 offset:16384
	v_exp_f32_e32 v145, v113
	v_exp_f32_e32 v146, v114
	v_exp_f32_e32 v147, v115
	ds_read_b128 v[112:115], v212 offset:24576
	v_mfma_f32_32x32x16_bf16 v[32:47], v[36:39], v[160:163], 0
	v_exp_f32_e32 v148, v116
	v_exp_f32_e32 v149, v117
	v_exp_f32_e32 v150, v118
	v_exp_f32_e32 v151, v119
	s_waitcnt lgkmcnt(0)
	v_mfma_f32_32x32x16_bf16 v[48:63], v[132:135], v[164:167], v[48:63]
	ds_read_b128 v[116:119], v213 offset:16384
	v_exp_f32_e32 v152, v120
	v_exp_f32_e32 v153, v121
	v_exp_f32_e32 v154, v122
	v_exp_f32_e32 v155, v123
	v_mfma_f32_32x32x16_bf16 v[32:47], v[136:139], v[164:167], v[32:47]
	ds_read_b128 v[120:123], v213 offset:24576
	v_exp_f32_e32 v156, v124
	v_exp_f32_e32 v157, v125
	v_exp_f32_e32 v158, v126
	v_exp_f32_e32 v159, v127
	v_mfma_f32_32x32x16_bf16 v[48:63], v[140:143], v[168:171], v[48:63]
	v_add_u32_e32 v132, s48, v206
	ds_read_b128 v[124:127], v132 offset:16384
	v_exp_f32_e32 v136, v96
	v_exp_f32_e32 v137, v97
	v_exp_f32_e32 v138, v98
	v_exp_f32_e32 v139, v99
	v_mfma_f32_32x32x16_bf16 v[32:47], v[112:115], v[168:171], v[32:47]
	ds_read_b128 v[96:99], v132 offset:20480
	v_exp_f32_e32 v140, v100
	v_exp_f32_e32 v141, v101
	v_exp_f32_e32 v142, v102
	v_exp_f32_e32 v143, v103
	s_waitcnt lgkmcnt(0)
	v_mfma_f32_32x32x16_bf16 v[48:63], v[116:119], v[172:175], v[48:63]
	ds_read_b128 v[100:103], v132 offset:24576
	v_exp_f32_e32 v178, v104
	v_exp_f32_e32 v179, v105
	v_exp_f32_e32 v180, v106
	v_exp_f32_e32 v181, v107
	v_mfma_f32_32x32x16_bf16 v[32:47], v[120:123], v[172:175], v[32:47]
	ds_read_b128 v[104:107], v132 offset:28672
	v_exp_f32_e32 v182, v108
	v_exp_f32_e32 v183, v109
	v_exp_f32_e32 v184, v110
	v_exp_f32_e32 v185, v111
	v_cvt_pk_bf16_f32 v108, v144, v145
	v_cvt_pk_bf16_f32 v109, v146, v147
	v_cvt_pk_bf16_f32 v110, v148, v149
	v_cvt_pk_bf16_f32 v111, v150, v151
	s_nop 1
	v_mfma_f32_32x32x16_bf16 v[80:95], v[124:127], v[108:111], v[80:95]
	v_xad_u32 v186, v206, 32, s48
	ds_read_b128 v[112:115], v186 offset:16384
	v_cvt_pk_bf16_f32 v116, v152, v153
	v_cvt_pk_bf16_f32 v117, v154, v155
	v_cvt_pk_bf16_f32 v118, v156, v157
	v_cvt_pk_bf16_f32 v119, v158, v159
	v_mfma_f32_32x32x16_bf16 v[64:79], v[96:99], v[108:111], v[64:79]
	ds_read_b128 v[120:123], v186 offset:20480
	v_pk_add_f32 v[126:127], v[150:151], v[146:147]
	v_pk_add_f32 v[124:125], v[148:149], v[144:145]
	s_waitcnt lgkmcnt(0)
	v_mfma_f32_32x32x16_bf16 v[16:31], v[100:103], v[108:111], v[16:31]
	ds_read_b128 v[132:135], v186 offset:24576
	v_add_f32_e64 v98, v154, v126
	v_add_f32_e64 v99, v155, v127
	v_add_f32_e64 v96, v152, v124
	v_add_f32_e64 v97, v153, v125
	v_pk_add_f32 v[98:99], v[158:159], v[98:99]
	v_pk_add_f32 v[96:97], v[156:157], v[96:97]
	v_mfma_f32_32x32x16_bf16 v[0:15], v[104:107], v[108:111], v[0:15]
	ds_read_b128 v[100:103], v186 offset:28672
	v_mfma_f32_32x32x16_bf16 v[80:95], v[112:115], v[116:119], v[80:95]
	v_xad_u32 v124, v206, 64, s48
	ds_read_b128 v[104:107], v124 offset:16384
	v_cvt_pk_bf16_f32 v108, v136, v137
	v_cvt_pk_bf16_f32 v109, v138, v139
	v_cvt_pk_bf16_f32 v110, v140, v141
	v_cvt_pk_bf16_f32 v111, v142, v143
	v_mfma_f32_32x32x16_bf16 v[64:79], v[120:123], v[116:119], v[64:79]
	ds_read_b128 v[112:115], v124 offset:20480
	v_add_f32_e64 v98, v138, v98
	v_add_f32_e64 v99, v139, v99
	v_add_f32_e64 v96, v136, v96
	v_add_f32_e64 v97, v137, v97
	v_pk_add_f32 v[98:99], v[142:143], v[98:99]
	v_pk_add_f32 v[96:97], v[140:141], v[96:97]
	s_waitcnt lgkmcnt(0)
	v_mfma_f32_32x32x16_bf16 v[16:31], v[132:135], v[116:119], v[16:31]
	ds_read_b128 v[120:123], v124 offset:24576
	v_add_f32_e64 v98, v180, v98
	v_add_f32_e64 v99, v181, v99
	v_add_f32_e64 v96, v178, v96
	v_add_f32_e64 v97, v179, v97
	v_pk_add_f32 v[98:99], v[184:185], v[98:99]
	v_pk_add_f32 v[96:97], v[182:183], v[96:97]
	v_mfma_f32_32x32x16_bf16 v[0:15], v[100:103], v[116:119], v[0:15]
	ds_read_b128 v[124:127], v124 offset:28672
	v_mfma_f32_32x32x16_bf16 v[80:95], v[104:107], v[108:111], v[80:95]
	v_add_u32_e32 v132, s48, v209
	ds_read_b128 v[100:103], v132 offset:16384
	v_cvt_pk_bf16_f32 v116, v178, v179
	v_cvt_pk_bf16_f32 v117, v180, v181
	v_cvt_pk_bf16_f32 v118, v182, v183
	v_cvt_pk_bf16_f32 v119, v184, v185
	v_mfma_f32_32x32x16_bf16 v[64:79], v[112:115], v[108:111], v[64:79]
	ds_read_b128 v[104:107], v132 offset:20480
	s_waitcnt lgkmcnt(0)
	v_mfma_f32_32x32x16_bf16 v[16:31], v[120:123], v[108:111], v[16:31]
	ds_read_b128 v[112:115], v132 offset:24576
	v_mfma_f32_32x32x16_bf16 v[0:15], v[124:127], v[108:111], v[0:15]
	ds_read_b128 v[120:123], v132 offset:28672
	v_mfma_f32_32x32x16_bf16 v[80:95], v[100:103], v[116:119], v[80:95]
	v_mfma_f32_32x32x16_bf16 v[64:79], v[104:107], v[116:119], v[64:79]
	s_waitcnt lgkmcnt(0)
	v_mfma_f32_32x32x16_bf16 v[16:31], v[112:115], v[116:119], v[16:31]
	v_mfma_f32_32x32x16_bf16 v[0:15], v[120:123], v[116:119], v[0:15]
	s_waitcnt vmcnt(4) lgkmcnt(0)
	v_add_f32_e32 v100, v128, v129
	v_add_f32_e32 v101, v130, v131
	v_add_f32_e32 v100, v100, v101
	v_add_f32_e32 v96, v96, v97
	v_add_f32_e32 v97, v98, v99
	s_barrier
	v_add_f32_e32 v100, v177, v100
	v_add_f32_e32 v96, v96, v97
	v_add_f32_e32 v177, v100, v96
	s_add_i32 s21, s21, 2
	s_addk_i32 s15, 0x80
	s_add_i32 s20, s20, 0x8000
	s_add_u32 s98, s98, 0x30000
	s_addc_u32 s99, s99, 0
	s_add_u32 s100, s100, 0x100
	s_addc_u32 s101, s101, 0
	s_lshl_b32 s46, s41, 14
	s_add_i32 s46, s58, s46
	s_mov_b32 m0, s46
	s_nop 0
	global_load_lds_dwordx4 v198, s[98:99]
	s_add_i32 m0, s46, 0x400
	s_nop 0
	global_load_lds_dwordx4 v194, s[98:99]
	s_add_i32 s48, s20, 0xffffc000
	s_and_b32 s48, s48, 0x8000
	s_add_i32 s48, s58, s48
	s_add_i32 m0, s48, 0xc000
	s_nop 0
	global_load_lds_dwordx4 v196, s[100:101]
	s_add_i32 m0, s48, 0xc400
	s_nop 0
	global_load_lds_dwordx4 v192, s[100:101]
	s_add_i32 s46, s41, 1
	s_cmp_lg_u32 s41, 2
	s_cselect_b32 s41, s46, 0
	s_lshl_b32 s46, s41, 14
	s_add_i32 s49, s46, 0
	s_add_i32 s46, s20, 0xffff4000
	ds_read_b128 v[96:99], v205 offset:32768
	ds_read_b128 v[100:103], v205 offset:40960
	s_waitcnt lgkmcnt(0)
	v_mfma_f32_32x32x16_bf16 v[112:127], v[96:99], v[160:163], 0
	ds_read_b128 v[128:131], v211 offset:32768
	ds_read_b128 v[132:135], v211 offset:40960
	ds_read_b128 v[136:139], v212 offset:32768
	s_and_b32 s46, s46, 0x8000
	s_add_i32 s48, s46, 0
	v_exp_f32_e32 v140, v48
	v_exp_f32_e32 v141, v49
	v_exp_f32_e32 v142, v50
	v_exp_f32_e32 v143, v51
	ds_read_b128 v[48:51], v212 offset:40960
	v_mfma_f32_32x32x16_bf16 v[96:111], v[100:103], v[160:163], 0
	v_exp_f32_e32 v144, v52
	v_exp_f32_e32 v145, v53
	v_exp_f32_e32 v146, v54
	v_exp_f32_e32 v147, v55
	s_waitcnt lgkmcnt(0)
	v_mfma_f32_32x32x16_bf16 v[112:127], v[128:131], v[164:167], v[112:127]
	ds_read_b128 v[52:55], v213 offset:32768
	v_exp_f32_e32 v148, v56
	v_exp_f32_e32 v149, v57
	v_exp_f32_e32 v150, v58
	v_exp_f32_e32 v151, v59
	v_mfma_f32_32x32x16_bf16 v[96:111], v[132:135], v[164:167], v[96:111]
	ds_read_b128 v[56:59], v213 offset:40960
	v_exp_f32_e32 v128, v60
	v_exp_f32_e32 v129, v61
	v_exp_f32_e32 v130, v62
	v_exp_f32_e32 v131, v63
	v_mfma_f32_32x32x16_bf16 v[112:127], v[136:139], v[168:171], v[112:127]
	v_add_u32_e32 v156, s48, v206
	ds_read_b128 v[60:63], v156 offset:49152
	v_exp_f32_e32 v132, v32
	v_exp_f32_e32 v133, v33
	v_exp_f32_e32 v134, v34
	v_exp_f32_e32 v135, v35
	v_mfma_f32_32x32x16_bf16 v[96:111], v[48:51], v[168:171], v[96:111]
	ds_read_b128 v[32:35], v156 offset:53248
	v_exp_f32_e32 v136, v36
	v_exp_f32_e32 v137, v37
	v_exp_f32_e32 v138, v38
	v_exp_f32_e32 v139, v39
	s_waitcnt lgkmcnt(0)
	v_mfma_f32_32x32x16_bf16 v[112:127], v[52:55], v[172:175], v[112:127]
	ds_read_b128 v[36:39], v156 offset:57344
	v_exp_f32_e32 v152, v40
	v_exp_f32_e32 v153, v41
	v_exp_f32_e32 v154, v42
	v_exp_f32_e32 v155, v43
	v_mfma_f32_32x32x16_bf16 v[96:111], v[56:59], v[172:175], v[96:111]
	ds_read_b128 v[40:43], v156 offset:61440
	v_exp_f32_e32 v156, v44
	v_exp_f32_e32 v157, v45
	v_exp_f32_e32 v158, v46
	v_exp_f32_e32 v159, v47
	v_cvt_pk_bf16_f32 v44, v140, v141
	v_cvt_pk_bf16_f32 v45, v142, v143
	v_cvt_pk_bf16_f32 v46, v144, v145
	v_cvt_pk_bf16_f32 v47, v146, v147
	s_nop 1
	v_mfma_f32_32x32x16_bf16 v[80:95], v[60:63], v[44:47], v[80:95]
	v_xad_u32 v178, v206, 32, s48
	ds_read_b128 v[48:51], v178 offset:49152
	v_cvt_pk_bf16_f32 v52, v148, v149
	v_cvt_pk_bf16_f32 v53, v150, v151
	v_cvt_pk_bf16_f32 v54, v128, v129
	v_cvt_pk_bf16_f32 v55, v130, v131
	v_mfma_f32_32x32x16_bf16 v[64:79], v[32:35], v[44:47], v[64:79]
	ds_read_b128 v[56:59], v178 offset:53248
	v_pk_add_f32 v[62:63], v[146:147], v[142:143]
	v_pk_add_f32 v[60:61], v[144:145], v[140:141]
	s_waitcnt lgkmcnt(0)
	v_mfma_f32_32x32x16_bf16 v[16:31], v[36:39], v[44:47], v[16:31]
	ds_read_b128 v[32:35], v178 offset:57344
	v_add_f32_e64 v62, v150, v62
	v_add_f32_e64 v63, v151, v63
	v_add_f32_e64 v60, v148, v60
	v_add_f32_e64 v61, v149, v61
	v_pk_add_f32 v[62:63], v[130:131], v[62:63]
	v_pk_add_f32 v[60:61], v[128:129], v[60:61]
	v_mfma_f32_32x32x16_bf16 v[0:15], v[40:43], v[44:47], v[0:15]
	ds_read_b128 v[36:39], v178 offset:61440
	v_mfma_f32_32x32x16_bf16 v[80:95], v[48:51], v[52:55], v[80:95]
	v_xad_u32 v140, v206, 64, s48
	ds_read_b128 v[40:43], v140 offset:49152
	v_cvt_pk_bf16_f32 v44, v132, v133
	v_cvt_pk_bf16_f32 v45, v134, v135
	v_cvt_pk_bf16_f32 v46, v136, v137
	v_cvt_pk_bf16_f32 v47, v138, v139
	v_mfma_f32_32x32x16_bf16 v[64:79], v[56:59], v[52:55], v[64:79]
	ds_read_b128 v[48:51], v140 offset:53248
	v_add_f32_e64 v62, v134, v62
	v_add_f32_e64 v63, v135, v63
	v_add_f32_e64 v60, v132, v60
	v_add_f32_e64 v61, v133, v61
	v_pk_add_f32 v[62:63], v[138:139], v[62:63]
	v_pk_add_f32 v[60:61], v[136:137], v[60:61]
	s_waitcnt lgkmcnt(0)
	v_mfma_f32_32x32x16_bf16 v[16:31], v[32:35], v[52:55], v[16:31]
	ds_read_b128 v[56:59], v140 offset:57344
	v_add_f32_e64 v62, v154, v62
	v_add_f32_e64 v63, v155, v63
	v_add_f32_e64 v60, v152, v60
	v_add_f32_e64 v61, v153, v61
	v_pk_add_f32 v[130:131], v[158:159], v[62:63]
	v_pk_add_f32 v[128:129], v[156:157], v[60:61]
	v_mfma_f32_32x32x16_bf16 v[0:15], v[36:39], v[52:55], v[0:15]
	ds_read_b128 v[32:35], v140 offset:61440
	v_mfma_f32_32x32x16_bf16 v[80:95], v[40:43], v[44:47], v[80:95]
	v_add_u32_e32 v60, s48, v209
	ds_read_b128 v[36:39], v60 offset:49152
	v_cvt_pk_bf16_f32 v52, v152, v153
	v_cvt_pk_bf16_f32 v53, v154, v155
	v_cvt_pk_bf16_f32 v54, v156, v157
	v_cvt_pk_bf16_f32 v55, v158, v159
	v_mfma_f32_32x32x16_bf16 v[64:79], v[48:51], v[44:47], v[64:79]
	ds_read_b128 v[40:43], v60 offset:53248
	s_waitcnt lgkmcnt(0)
	v_mfma_f32_32x32x16_bf16 v[16:31], v[56:59], v[44:47], v[16:31]
	ds_read_b128 v[48:51], v60 offset:57344
	v_mfma_f32_32x32x16_bf16 v[0:15], v[32:35], v[44:47], v[0:15]
	ds_read_b128 v[56:59], v60 offset:61440
	v_mfma_f32_32x32x16_bf16 v[80:95], v[36:39], v[52:55], v[80:95]
	v_mfma_f32_32x32x16_bf16 v[64:79], v[40:43], v[52:55], v[64:79]
	s_waitcnt lgkmcnt(0)
	v_mfma_f32_32x32x16_bf16 v[16:31], v[48:51], v[52:55], v[16:31]
	v_mfma_f32_32x32x16_bf16 v[0:15], v[56:59], v[52:55], v[0:15]
	s_waitcnt vmcnt(4) lgkmcnt(0)
	s_barrier
	s_add_u32 s68, s98, 0x18000
	s_addc_u32 s69, s99, 0
	s_add_i32 s49, s49, s57
	s_mov_b32 m0, s49
	s_nop 0
	global_load_lds_dwordx4 v198, s[68:69]
	s_add_i32 m0, s49, 0x400
	s_nop 0
	global_load_lds_dwordx4 v194, s[68:69]
	s_add_u32 s44, s100, 0x80
	s_addc_u32 s45, s101, 0
	s_and_b32 s49, s20, 0xc000
	s_add_i32 s49, s58, s49
	s_add_i32 m0, s49, 0xc000
	s_nop 0
	global_load_lds_dwordx4 v196, s[44:45]
	s_add_i32 m0, s49, 0xc400
	s_nop 0
	global_load_lds_dwordx4 v192, s[44:45]
	s_add_i32 s48, s48, 0xc000
	s_add_i32 s44, s41, 1
	s_cmp_lg_u32 s41, 2
	s_cselect_b32 s41, s44, 0
	s_lshl_b32 s44, s41, 14
	s_add_i32 s44, s44, 0
	v_exp_f32_e32 v144, v112
	ds_read_b128 v[32:35], v205
	ds_read_b128 v[36:39], v205 offset:8192
	s_waitcnt lgkmcnt(0)
	v_mfma_f32_32x32x16_bf16 v[48:63], v[32:35], v[160:163], 0
	ds_read_b128 v[132:135], v211
	ds_read_b128 v[136:139], v211 offset:8192
	ds_read_b128 v[140:143], v212
	v_exp_f32_e32 v145, v113
	v_exp_f32_e32 v146, v114
	v_exp_f32_e32 v147, v115
	ds_read_b128 v[112:115], v212 offset:8192
	v_mfma_f32_32x32x16_bf16 v[32:47], v[36:39], v[160:163], 0
	v_exp_f32_e32 v148, v116
	v_exp_f32_e32 v149, v117
	v_exp_f32_e32 v150, v118
	v_exp_f32_e32 v151, v119
	s_waitcnt lgkmcnt(0)
	v_mfma_f32_32x32x16_bf16 v[48:63], v[132:135], v[164:167], v[48:63]
	ds_read_b128 v[116:119], v213
	v_exp_f32_e32 v152, v120
	v_exp_f32_e32 v153, v121
	v_exp_f32_e32 v154, v122
	v_exp_f32_e32 v155, v123
	v_mfma_f32_32x32x16_bf16 v[32:47], v[136:139], v[164:167], v[32:47]
	ds_read_b128 v[120:123], v213 offset:8192
	v_exp_f32_e32 v156, v124
	v_exp_f32_e32 v157, v125
	v_exp_f32_e32 v158, v126
	v_exp_f32_e32 v159, v127
	v_mfma_f32_32x32x16_bf16 v[48:63], v[140:143], v[168:171], v[48:63]
	v_add_u32_e32 v132, s48, v206
	ds_read_b128 v[124:127], v132 offset:16384
	v_exp_f32_e32 v136, v96
	v_exp_f32_e32 v137, v97
	v_exp_f32_e32 v138, v98
	v_exp_f32_e32 v139, v99
	v_mfma_f32_32x32x16_bf16 v[32:47], v[112:115], v[168:171], v[32:47]
	ds_read_b128 v[96:99], v132 offset:20480
	v_exp_f32_e32 v140, v100
	v_exp_f32_e32 v141, v101
	v_exp_f32_e32 v142, v102
	v_exp_f32_e32 v143, v103
	s_waitcnt lgkmcnt(0)
	v_mfma_f32_32x32x16_bf16 v[48:63], v[116:119], v[172:175], v[48:63]
	ds_read_b128 v[100:103], v132 offset:24576
	v_exp_f32_e32 v178, v104
	v_exp_f32_e32 v179, v105
	v_exp_f32_e32 v180, v106
	v_exp_f32_e32 v181, v107
	v_mfma_f32_32x32x16_bf16 v[32:47], v[120:123], v[172:175], v[32:47]
	ds_read_b128 v[104:107], v132 offset:28672
	v_exp_f32_e32 v182, v108
	v_exp_f32_e32 v183, v109
	v_exp_f32_e32 v184, v110
	v_exp_f32_e32 v185, v111
	v_cvt_pk_bf16_f32 v108, v144, v145
	v_cvt_pk_bf16_f32 v109, v146, v147
	v_cvt_pk_bf16_f32 v110, v148, v149
	v_cvt_pk_bf16_f32 v111, v150, v151
	s_nop 1
	v_mfma_f32_32x32x16_bf16 v[80:95], v[124:127], v[108:111], v[80:95]
	v_xad_u32 v186, v206, 32, s48
	ds_read_b128 v[112:115], v186 offset:16384
	v_cvt_pk_bf16_f32 v116, v152, v153
	v_cvt_pk_bf16_f32 v117, v154, v155
	v_cvt_pk_bf16_f32 v118, v156, v157
	v_cvt_pk_bf16_f32 v119, v158, v159
	v_mfma_f32_32x32x16_bf16 v[64:79], v[96:99], v[108:111], v[64:79]
	ds_read_b128 v[120:123], v186 offset:20480
	v_pk_add_f32 v[126:127], v[150:151], v[146:147]
	v_pk_add_f32 v[124:125], v[148:149], v[144:145]
	s_waitcnt lgkmcnt(0)
	v_mfma_f32_32x32x16_bf16 v[16:31], v[100:103], v[108:111], v[16:31]
	ds_read_b128 v[132:135], v186 offset:24576
	v_add_f32_e64 v98, v154, v126
	v_add_f32_e64 v99, v155, v127
	v_add_f32_e64 v96, v152, v124
	v_add_f32_e64 v97, v153, v125
	v_pk_add_f32 v[98:99], v[158:159], v[98:99]
	v_pk_add_f32 v[96:97], v[156:157], v[96:97]
	v_mfma_f32_32x32x16_bf16 v[0:15], v[104:107], v[108:111], v[0:15]
	ds_read_b128 v[100:103], v186 offset:28672
	v_mfma_f32_32x32x16_bf16 v[80:95], v[112:115], v[116:119], v[80:95]
	v_xad_u32 v124, v206, 64, s48
	ds_read_b128 v[104:107], v124 offset:16384
	v_cvt_pk_bf16_f32 v108, v136, v137
	v_cvt_pk_bf16_f32 v109, v138, v139
	v_cvt_pk_bf16_f32 v110, v140, v141
	v_cvt_pk_bf16_f32 v111, v142, v143
	v_mfma_f32_32x32x16_bf16 v[64:79], v[120:123], v[116:119], v[64:79]
	ds_read_b128 v[112:115], v124 offset:20480
	v_add_f32_e64 v98, v138, v98
	v_add_f32_e64 v99, v139, v99
	v_add_f32_e64 v96, v136, v96
	v_add_f32_e64 v97, v137, v97
	v_pk_add_f32 v[98:99], v[142:143], v[98:99]
	v_pk_add_f32 v[96:97], v[140:141], v[96:97]
	s_waitcnt lgkmcnt(0)
	v_mfma_f32_32x32x16_bf16 v[16:31], v[132:135], v[116:119], v[16:31]
	ds_read_b128 v[120:123], v124 offset:24576
	v_add_f32_e64 v98, v180, v98
	v_add_f32_e64 v99, v181, v99
	v_add_f32_e64 v96, v178, v96
	v_add_f32_e64 v97, v179, v97
	v_pk_add_f32 v[98:99], v[184:185], v[98:99]
	v_pk_add_f32 v[96:97], v[182:183], v[96:97]
	v_mfma_f32_32x32x16_bf16 v[0:15], v[100:103], v[116:119], v[0:15]
	ds_read_b128 v[124:127], v124 offset:28672
	v_mfma_f32_32x32x16_bf16 v[80:95], v[104:107], v[108:111], v[80:95]
	v_add_u32_e32 v132, s48, v209
	ds_read_b128 v[100:103], v132 offset:16384
	v_cvt_pk_bf16_f32 v116, v178, v179
	v_cvt_pk_bf16_f32 v117, v180, v181
	v_cvt_pk_bf16_f32 v118, v182, v183
	v_cvt_pk_bf16_f32 v119, v184, v185
	v_mfma_f32_32x32x16_bf16 v[64:79], v[112:115], v[108:111], v[64:79]
	ds_read_b128 v[104:107], v132 offset:20480
	s_waitcnt lgkmcnt(0)
	v_mfma_f32_32x32x16_bf16 v[16:31], v[120:123], v[108:111], v[16:31]
	ds_read_b128 v[112:115], v132 offset:24576
	v_mfma_f32_32x32x16_bf16 v[0:15], v[124:127], v[108:111], v[0:15]
	ds_read_b128 v[120:123], v132 offset:28672
	v_mfma_f32_32x32x16_bf16 v[80:95], v[100:103], v[116:119], v[80:95]
	v_mfma_f32_32x32x16_bf16 v[64:79], v[104:107], v[116:119], v[64:79]
	s_waitcnt lgkmcnt(0)
	v_mfma_f32_32x32x16_bf16 v[16:31], v[112:115], v[116:119], v[16:31]
	v_mfma_f32_32x32x16_bf16 v[0:15], v[120:123], v[116:119], v[0:15]
	s_waitcnt vmcnt(4) lgkmcnt(0)
	v_add_f32_e32 v100, v128, v129
	v_add_f32_e32 v101, v130, v131
	v_add_f32_e32 v100, v100, v101
	v_add_f32_e32 v96, v96, v97
	v_add_f32_e32 v97, v98, v99
	s_barrier
	v_add_f32_e32 v100, v177, v100
	v_add_f32_e32 v96, v96, v97
	v_add_f32_e32 v177, v100, v96
	s_add_i32 s21, s21, 2
	s_addk_i32 s15, 0x80
	s_add_i32 s20, s20, 0x8000
	s_add_u32 s98, s98, 0x30000
	s_addc_u32 s99, s99, 0
	s_add_u32 s100, s100, 0x100
	s_addc_u32 s101, s101, 0
	s_cmp_lt_u32 s21, 56
	s_cbranch_scc1 .Lst0_u3
	s_cmp_lt_u32 s21, 60
	s_cbranch_scc1 .Lst0_single
.Lst0_exit:
	s_branch .LBB0_936

.Lst1_loop:
	s_cmp_lg_u32 s48, 0
	s_cbranch_scc1 .Lst1_single
	s_cmp_lt_u32 s47, 56
	s_cbranch_scc1 .Lst1_u3

.Lst1_u3:
	s_lshl_b32 s49, s48, 14
	s_add_i32 s49, s58, s49
	s_mov_b32 m0, s49
	s_nop 0
	global_load_lds_dwordx4 v198, s[98:99]
	s_add_i32 m0, s49, 0x400
	s_nop 0
	global_load_lds_dwordx4 v194, s[98:99]
	s_add_i32 s49, s46, 0xffffc000
	s_and_b32 s49, s49, 0xc000
	s_add_i32 s49, s58, s49
	s_add_i32 m0, s49, 0xc000
	s_nop 0
	global_load_lds_dwordx4 v196, s[100:101]
	s_add_i32 m0, s49, 0xc400
	s_add_i32 s44, s48, 1
	global_load_lds_dwordx4 v192, s[100:101]
	s_cmp_lg_u32 s48, 2
	s_cselect_b32 s48, s44, 0
	s_lshl_b32 s44, s48, 14
	s_and_b32 s49, s46, 0xc000
	s_add_i32 s68, s44, 0
	s_add_i32 s44, s49, 0
	v_add_u32_e32 v156, s44, v206
	ds_read_b128 v[140:143], v156 offset:49152
	ds_read_b128 v[148:151], v156 offset:53248
	ds_read_b128 v[152:155], v156 offset:57344
	ds_read_b128 v[156:159], v156 offset:61440
	s_waitcnt lgkmcnt(0)
	v_mfma_f32_32x32x16_bf16 v[80:95], v[140:143], v[144:147], v[80:95]
	v_xad_u32 v177, v206, 32, s44
	ds_read_b128 v[140:143], v177 offset:49152
	v_mfma_f32_32x32x16_bf16 v[64:79], v[148:151], v[144:147], v[64:79]
	ds_read_b128 v[148:151], v177 offset:53248
	v_mfma_f32_32x32x16_bf16 v[16:31], v[152:155], v[144:147], v[16:31]
	ds_read_b128 v[152:155], v177 offset:57344
	v_mfma_f32_32x32x16_bf16 v[0:15], v[156:159], v[144:147], v[0:15]
	ds_read_b128 v[144:147], v177 offset:61440
	s_waitcnt lgkmcnt(0)
	v_mfma_f32_32x32x16_bf16 v[80:95], v[140:143], v[128:131], v[80:95]
	v_xad_u32 v156, v206, 64, s44
	ds_read_b128 v[140:143], v156 offset:49152
	v_mfma_f32_32x32x16_bf16 v[64:79], v[148:151], v[128:131], v[64:79]
	ds_read_b128 v[148:151], v156 offset:53248
	v_mfma_f32_32x32x16_bf16 v[16:31], v[152:155], v[128:131], v[16:31]
	ds_read_b128 v[152:155], v156 offset:57344
	v_mfma_f32_32x32x16_bf16 v[0:15], v[144:147], v[128:131], v[0:15]
	ds_read_b128 v[128:131], v156 offset:61440
	s_waitcnt lgkmcnt(0)
	v_mfma_f32_32x32x16_bf16 v[80:95], v[140:143], v[132:135], v[80:95]
	v_add_u32_e32 v156, s44, v209
	ds_read_b128 v[140:143], v156 offset:49152
	v_mfma_f32_32x32x16_bf16 v[64:79], v[148:151], v[132:135], v[64:79]
	ds_read_b128 v[144:147], v156 offset:53248
	v_mfma_f32_32x32x16_bf16 v[16:31], v[152:155], v[132:135], v[16:31]
	ds_read_b128 v[148:151], v156 offset:57344
	v_mfma_f32_32x32x16_bf16 v[0:15], v[128:131], v[132:135], v[0:15]
	ds_read_b128 v[128:131], v156 offset:61440
	s_waitcnt lgkmcnt(0)
	v_mfma_f32_32x32x16_bf16 v[80:95], v[140:143], v[136:139], v[80:95]
	ds_read_b128 v[132:135], v205 offset:16384
	v_mfma_f32_32x32x16_bf16 v[64:79], v[144:147], v[136:139], v[64:79]
	ds_read_b128 v[140:143], v205 offset:24576
	v_mfma_f32_32x32x16_bf16 v[16:31], v[148:151], v[136:139], v[16:31]
	ds_read_b128 v[176:179], v211 offset:16384
	v_mfma_f32_32x32x16_bf16 v[0:15], v[128:131], v[136:139], v[0:15]
	ds_read_b128 v[182:185], v211 offset:24576
	s_waitcnt lgkmcnt(0)
	v_mfma_f32_32x32x16_bf16 v[144:159], v[132:135], v[160:163], 0
	ds_read_b128 v[186:189], v212 offset:16384
	v_exp_f32_e32 v220, v112
	v_exp_f32_e32 v221, v113
	v_exp_f32_e32 v222, v114
	v_exp_f32_e32 v223, v115
	v_mfma_f32_32x32x16_bf16 v[128:143], v[140:143], v[160:163], 0
	ds_read_b128 v[216:219], v212 offset:24576
	v_exp_f32_e32 v224, v116
	v_exp_f32_e32 v225, v117
	v_exp_f32_e32 v226, v118
	v_exp_f32_e32 v227, v119
	v_mfma_f32_32x32x16_bf16 v[144:159], v[176:179], v[164:167], v[144:159]
	ds_read_b128 v[116:119], v213 offset:16384
	v_exp_f32_e32 v228, v120
	v_exp_f32_e32 v229, v121
	v_exp_f32_e32 v230, v122
	v_exp_f32_e32 v231, v123
	v_cvt_pk_bf16_f32 v112, v220, v221
	v_cvt_pk_bf16_f32 v113, v222, v223
	v_cvt_pk_bf16_f32 v114, v224, v225
	v_cvt_pk_bf16_f32 v115, v226, v227
	v_pk_add_f32 v[122:123], v[226:227], v[222:223]
	v_pk_add_f32 v[120:121], v[224:225], v[220:221]
	v_mfma_f32_32x32x16_bf16 v[128:143], v[182:185], v[164:167], v[128:143]
	ds_read_b128 v[176:179], v213 offset:24576
	v_exp_f32_e32 v124, v124
	v_exp_f32_e32 v125, v125
	v_exp_f32_e32 v126, v126
	v_exp_f32_e32 v127, v127
	s_waitcnt lgkmcnt(0)
	v_mfma_f32_32x32x16_bf16 v[144:159], v[186:189], v[168:171], v[144:159]
	v_add_f32_e64 v122, v230, v122
	v_add_f32_e64 v123, v231, v123
	v_add_f32_e64 v120, v228, v120
	v_add_f32_e64 v121, v229, v121
	v_exp_f32_e32 v182, v96
	v_exp_f32_e32 v183, v97
	v_exp_f32_e32 v184, v98
	v_exp_f32_e32 v185, v99
	v_cvt_pk_bf16_f32 v96, v228, v229
	v_cvt_pk_bf16_f32 v97, v230, v231
	v_cvt_pk_bf16_f32 v98, v124, v125
	v_cvt_pk_bf16_f32 v99, v126, v127
	v_pk_add_f32 v[122:123], v[126:127], v[122:123]
	v_pk_add_f32 v[120:121], v[124:125], v[120:121]
	v_mfma_f32_32x32x16_bf16 v[128:143], v[216:219], v[168:171], v[128:143]
	v_exp_f32_e32 v124, v100
	v_exp_f32_e32 v125, v101
	v_exp_f32_e32 v126, v102
	v_exp_f32_e32 v127, v103
	v_mfma_f32_32x32x16_bf16 v[144:159], v[116:119], v[172:175], v[144:159]
	v_exp_f32_e32 v186, v104
	v_exp_f32_e32 v187, v105
	v_exp_f32_e32 v188, v106
	v_exp_f32_e32 v189, v107
	v_pk_add_f32 v[106:107], v[184:185], v[122:123]
	v_pk_add_f32 v[104:105], v[182:183], v[120:121]
	v_cvt_pk_bf16_f32 v100, v182, v183
	v_cvt_pk_bf16_f32 v101, v184, v185
	v_cvt_pk_bf16_f32 v102, v124, v125
	v_cvt_pk_bf16_f32 v103, v126, v127
	v_pk_add_f32 v[118:119], v[126:127], v[106:107]
	v_pk_add_f32 v[116:117], v[124:125], v[104:105]
	v_mfma_f32_32x32x16_bf16 v[128:143], v[176:179], v[172:175], v[128:143]
	v_exp_f32_e32 v120, v108
	v_exp_f32_e32 v121, v109
	v_exp_f32_e32 v122, v110
	v_exp_f32_e32 v123, v111
	v_pk_add_f32 v[110:111], v[188:189], v[118:119]
	v_pk_add_f32 v[108:109], v[186:187], v[116:117]
	v_cvt_pk_bf16_f32 v104, v186, v187
	v_cvt_pk_bf16_f32 v105, v188, v189
	v_cvt_pk_bf16_f32 v106, v120, v121
	v_cvt_pk_bf16_f32 v107, v122, v123
	v_pk_add_f32 v[178:179], v[122:123], v[110:111]
	v_pk_add_f32 v[176:177], v[120:121], v[108:109]
	s_waitcnt vmcnt(4) lgkmcnt(0)
	s_barrier
	s_add_u32 s70, s98, 0x18000
	s_addc_u32 s71, s99, 0
	s_add_i32 s68, s68, s57
	s_mov_b32 m0, s68
	s_nop 0
	global_load_lds_dwordx4 v198, s[70:71]
	s_add_i32 m0, s68, 0x400
	s_nop 0
	global_load_lds_dwordx4 v194, s[70:71]
	s_add_u32 s2, s100, 0x80
	s_addc_u32 s3, s101, 0
	s_add_i32 s49, s58, s49
	s_add_i32 m0, s49, 0xc000
	s_nop 0
	global_load_lds_dwordx4 v196, s[2:3]
	s_add_i32 m0, s49, 0xc400
	s_nop 0
	global_load_lds_dwordx4 v192, s[2:3]
	s_add_i32 s2, s46, 0xffff4000
	s_add_i32 s3, s48, 1
	s_cmp_lg_u32 s48, 2
	s_cselect_b32 s48, s3, 0
	s_and_b32 s2, s2, 0xc000
	s_add_i32 s2, s2, 0
	s_lshl_b32 s3, s48, 14
	v_add_u32_e32 v124, s2, v206
	ds_read_b128 v[108:111], v124 offset:49152
	ds_read_b128 v[116:119], v124 offset:53248
	ds_read_b128 v[120:123], v124 offset:57344
	ds_read_b128 v[124:127], v124 offset:61440
	s_waitcnt lgkmcnt(0)
	v_mfma_f32_32x32x16_bf16 v[80:95], v[108:111], v[112:115], v[80:95]
	v_xad_u32 v182, v206, 32, s2
	ds_read_b128 v[108:111], v182 offset:49152
	s_add_i32 s3, s3, 0
	v_mfma_f32_32x32x16_bf16 v[64:79], v[116:119], v[112:115], v[64:79]
	ds_read_b128 v[116:119], v182 offset:53248
	v_mfma_f32_32x32x16_bf16 v[16:31], v[120:123], v[112:115], v[16:31]
	ds_read_b128 v[120:123], v182 offset:57344
	v_mfma_f32_32x32x16_bf16 v[0:15], v[124:127], v[112:115], v[0:15]
	ds_read_b128 v[112:115], v182 offset:61440
	s_waitcnt lgkmcnt(0)
	v_mfma_f32_32x32x16_bf16 v[80:95], v[108:111], v[96:99], v[80:95]
	v_xad_u32 v124, v206, 64, s2
	ds_read_b128 v[108:111], v124 offset:49152
	v_mfma_f32_32x32x16_bf16 v[64:79], v[116:119], v[96:99], v[64:79]
	ds_read_b128 v[116:119], v124 offset:53248
	v_mfma_f32_32x32x16_bf16 v[16:31], v[120:123], v[96:99], v[16:31]
	ds_read_b128 v[120:123], v124 offset:57344
	v_mfma_f32_32x32x16_bf16 v[0:15], v[112:115], v[96:99], v[0:15]
	ds_read_b128 v[96:99], v124 offset:61440
	s_waitcnt lgkmcnt(0)
	v_mfma_f32_32x32x16_bf16 v[80:95], v[108:111], v[100:103], v[80:95]
	v_add_u32_e32 v124, s2, v209
	ds_read_b128 v[108:111], v124 offset:49152
	v_mfma_f32_32x32x16_bf16 v[64:79], v[116:119], v[100:103], v[64:79]
	ds_read_b128 v[112:115], v124 offset:53248
	v_mfma_f32_32x32x16_bf16 v[16:31], v[120:123], v[100:103], v[16:31]
	ds_read_b128 v[116:119], v124 offset:57344
	v_mfma_f32_32x32x16_bf16 v[0:15], v[96:99], v[100:103], v[0:15]
	ds_read_b128 v[120:123], v124 offset:61440
	s_waitcnt lgkmcnt(0)
	v_mfma_f32_32x32x16_bf16 v[80:95], v[108:111], v[104:107], v[80:95]
	ds_read_b128 v[96:99], v205 offset:32768
	v_mfma_f32_32x32x16_bf16 v[64:79], v[112:115], v[104:107], v[64:79]
	ds_read_b128 v[100:103], v205 offset:40960
	v_mfma_f32_32x32x16_bf16 v[16:31], v[116:119], v[104:107], v[16:31]
	ds_read_b128 v[182:185], v211 offset:32768
	v_mfma_f32_32x32x16_bf16 v[0:15], v[120:123], v[104:107], v[0:15]
	ds_read_b128 v[186:189], v211 offset:40960
	s_waitcnt lgkmcnt(0)
	v_mfma_f32_32x32x16_bf16 v[112:127], v[96:99], v[160:163], 0
	ds_read_b128 v[216:219], v212 offset:32768
	v_exp_f32_e32 v224, v144
	v_exp_f32_e32 v225, v145
	v_exp_f32_e32 v226, v146
	v_exp_f32_e32 v227, v147
	ds_read_b128 v[220:223], v212 offset:40960
	v_mfma_f32_32x32x16_bf16 v[96:111], v[100:103], v[160:163], 0
	v_exp_f32_e32 v228, v148
	v_exp_f32_e32 v229, v149
	v_exp_f32_e32 v230, v150
	v_exp_f32_e32 v231, v151
	v_mfma_f32_32x32x16_bf16 v[112:127], v[182:185], v[164:167], v[112:127]
	ds_read_b128 v[148:151], v213 offset:32768
	v_exp_f32_e32 v232, v152
	v_exp_f32_e32 v233, v153
	v_exp_f32_e32 v234, v154
	v_exp_f32_e32 v235, v155
	v_cvt_pk_bf16_f32 v144, v224, v225
	v_cvt_pk_bf16_f32 v145, v226, v227
	v_cvt_pk_bf16_f32 v146, v228, v229
	v_cvt_pk_bf16_f32 v147, v230, v231
	v_pk_add_f32 v[154:155], v[230:231], v[226:227]
	v_pk_add_f32 v[152:153], v[228:229], v[224:225]
	v_mfma_f32_32x32x16_bf16 v[96:111], v[186:189], v[164:167], v[96:111]
	ds_read_b128 v[182:185], v213 offset:40960
	v_exp_f32_e32 v156, v156
	v_exp_f32_e32 v157, v157
	v_exp_f32_e32 v158, v158
	v_exp_f32_e32 v159, v159
	s_waitcnt lgkmcnt(0)
	v_mfma_f32_32x32x16_bf16 v[112:127], v[216:219], v[168:171], v[112:127]
	v_add_f32_e64 v154, v234, v154
	v_add_f32_e64 v155, v235, v155
	v_add_f32_e64 v152, v232, v152
	v_add_f32_e64 v153, v233, v153
	v_exp_f32_e32 v186, v128
	v_exp_f32_e32 v187, v129
	v_exp_f32_e32 v188, v130
	v_exp_f32_e32 v189, v131
	v_cvt_pk_bf16_f32 v128, v232, v233
	v_cvt_pk_bf16_f32 v129, v234, v235
	v_cvt_pk_bf16_f32 v130, v156, v157
	v_cvt_pk_bf16_f32 v131, v158, v159
	v_pk_add_f32 v[154:155], v[158:159], v[154:155]
	v_pk_add_f32 v[152:153], v[156:157], v[152:153]
	v_mfma_f32_32x32x16_bf16 v[96:111], v[220:223], v[168:171], v[96:111]
	v_exp_f32_e32 v156, v132
	v_exp_f32_e32 v157, v133
	v_exp_f32_e32 v158, v134
	v_exp_f32_e32 v159, v135
	v_mfma_f32_32x32x16_bf16 v[112:127], v[148:151], v[172:175], v[112:127]
	v_exp_f32_e32 v216, v136
	v_exp_f32_e32 v217, v137
	v_exp_f32_e32 v218, v138
	v_exp_f32_e32 v219, v139
	v_pk_add_f32 v[138:139], v[188:189], v[154:155]
	v_pk_add_f32 v[136:137], v[186:187], v[152:153]
	v_cvt_pk_bf16_f32 v132, v186, v187
	v_cvt_pk_bf16_f32 v133, v188, v189
	v_cvt_pk_bf16_f32 v134, v156, v157
	v_cvt_pk_bf16_f32 v135, v158, v159
	v_pk_add_f32 v[150:151], v[158:159], v[138:139]
	v_pk_add_f32 v[148:149], v[156:157], v[136:137]
	v_mfma_f32_32x32x16_bf16 v[96:111], v[182:185], v[172:175], v[96:111]
	v_exp_f32_e32 v152, v140
	v_exp_f32_e32 v153, v141
	v_exp_f32_e32 v154, v142
	v_exp_f32_e32 v155, v143
	v_pk_add_f32 v[142:143], v[218:219], v[150:151]
	v_pk_add_f32 v[140:141], v[216:217], v[148:149]
	v_cvt_pk_bf16_f32 v136, v216, v217
	v_cvt_pk_bf16_f32 v137, v218, v219
	v_cvt_pk_bf16_f32 v138, v152, v153
	v_cvt_pk_bf16_f32 v139, v154, v155
	v_pk_add_f32 v[142:143], v[154:155], v[142:143]
	v_pk_add_f32 v[140:141], v[152:153], v[140:141]
	s_waitcnt vmcnt(4) lgkmcnt(0)
	v_add_f32_e32 v148, v176, v177
	v_add_f32_e32 v149, v178, v179
	v_add_f32_e32 v148, v148, v149
	v_add_f32_e32 v140, v140, v141
	v_add_f32_e32 v141, v142, v143
	s_barrier
	v_add_f32_e32 v148, v180, v148
	v_add_f32_e32 v140, v140, v141
	v_add_f32_e32 v180, v148, v140
	s_add_i32 s47, s47, 2
	s_addk_i32 s41, 0x80
	s_add_i32 s46, s46, 0x8000
	s_add_u32 s98, s98, 0x30000
	s_addc_u32 s99, s99, 0
	s_add_u32 s100, s100, 0x100
	s_addc_u32 s101, s101, 0
	s_lshl_b32 s49, s48, 14
	s_add_i32 s49, s58, s49
	s_mov_b32 m0, s49
	s_nop 0
	global_load_lds_dwordx4 v198, s[98:99]
	s_add_i32 m0, s49, 0x400
	s_nop 0
	global_load_lds_dwordx4 v194, s[98:99]
	s_add_i32 s49, s46, 0xffffc000
	s_and_b32 s49, s49, 0xc000
	s_add_i32 s49, s58, s49
	s_add_i32 m0, s49, 0xc000
	s_nop 0
	global_load_lds_dwordx4 v196, s[100:101]
	s_add_i32 m0, s49, 0xc400
	s_add_i32 s44, s48, 1
	global_load_lds_dwordx4 v192, s[100:101]
	s_cmp_lg_u32 s48, 2
	s_cselect_b32 s48, s44, 0
	s_lshl_b32 s44, s48, 14
	s_and_b32 s49, s46, 0xc000
	s_add_i32 s68, s44, 0
	s_add_i32 s44, s49, 0
	v_add_u32_e32 v156, s44, v206
	ds_read_b128 v[140:143], v156 offset:49152
	ds_read_b128 v[148:151], v156 offset:53248
	ds_read_b128 v[152:155], v156 offset:57344
	ds_read_b128 v[156:159], v156 offset:61440
	s_waitcnt lgkmcnt(0)
	v_mfma_f32_32x32x16_bf16 v[80:95], v[140:143], v[144:147], v[80:95]
	v_xad_u32 v177, v206, 32, s44
	ds_read_b128 v[140:143], v177 offset:49152
	v_mfma_f32_32x32x16_bf16 v[64:79], v[148:151], v[144:147], v[64:79]
	ds_read_b128 v[148:151], v177 offset:53248
	v_mfma_f32_32x32x16_bf16 v[16:31], v[152:155], v[144:147], v[16:31]
	ds_read_b128 v[152:155], v177 offset:57344
	v_mfma_f32_32x32x16_bf16 v[0:15], v[156:159], v[144:147], v[0:15]
	ds_read_b128 v[144:147], v177 offset:61440
	s_waitcnt lgkmcnt(0)
	v_mfma_f32_32x32x16_bf16 v[80:95], v[140:143], v[128:131], v[80:95]
	v_xad_u32 v156, v206, 64, s44
	ds_read_b128 v[140:143], v156 offset:49152
	v_mfma_f32_32x32x16_bf16 v[64:79], v[148:151], v[128:131], v[64:79]
	ds_read_b128 v[148:151], v156 offset:53248
	v_mfma_f32_32x32x16_bf16 v[16:31], v[152:155], v[128:131], v[16:31]
	ds_read_b128 v[152:155], v156 offset:57344
	v_mfma_f32_32x32x16_bf16 v[0:15], v[144:147], v[128:131], v[0:15]
	ds_read_b128 v[128:131], v156 offset:61440
	s_waitcnt lgkmcnt(0)
	v_mfma_f32_32x32x16_bf16 v[80:95], v[140:143], v[132:135], v[80:95]
	v_add_u32_e32 v156, s44, v209
	ds_read_b128 v[140:143], v156 offset:49152
	v_mfma_f32_32x32x16_bf16 v[64:79], v[148:151], v[132:135], v[64:79]
	ds_read_b128 v[144:147], v156 offset:53248
	v_mfma_f32_32x32x16_bf16 v[16:31], v[152:155], v[132:135], v[16:31]
	ds_read_b128 v[148:151], v156 offset:57344
	v_mfma_f32_32x32x16_bf16 v[0:15], v[128:131], v[132:135], v[0:15]
	ds_read_b128 v[128:131], v156 offset:61440
	s_waitcnt lgkmcnt(0)
	v_mfma_f32_32x32x16_bf16 v[80:95], v[140:143], v[136:139], v[80:95]
	ds_read_b128 v[132:135], v205
	v_mfma_f32_32x32x16_bf16 v[64:79], v[144:147], v[136:139], v[64:79]
	ds_read_b128 v[140:143], v205 offset:8192
	v_mfma_f32_32x32x16_bf16 v[16:31], v[148:151], v[136:139], v[16:31]
	ds_read_b128 v[176:179], v211
	v_mfma_f32_32x32x16_bf16 v[0:15], v[128:131], v[136:139], v[0:15]
	ds_read_b128 v[182:185], v211 offset:8192
	s_waitcnt lgkmcnt(0)
	v_mfma_f32_32x32x16_bf16 v[144:159], v[132:135], v[160:163], 0
	ds_read_b128 v[186:189], v212
	v_exp_f32_e32 v220, v112
	v_exp_f32_e32 v221, v113
	v_exp_f32_e32 v222, v114
	v_exp_f32_e32 v223, v115
	v_mfma_f32_32x32x16_bf16 v[128:143], v[140:143], v[160:163], 0
	ds_read_b128 v[216:219], v212 offset:8192
	v_exp_f32_e32 v224, v116
	v_exp_f32_e32 v225, v117
	v_exp_f32_e32 v226, v118
	v_exp_f32_e32 v227, v119
	v_mfma_f32_32x32x16_bf16 v[144:159], v[176:179], v[164:167], v[144:159]
	ds_read_b128 v[116:119], v213
	v_exp_f32_e32 v228, v120
	v_exp_f32_e32 v229, v121
	v_exp_f32_e32 v230, v122
	v_exp_f32_e32 v231, v123
	v_cvt_pk_bf16_f32 v112, v220, v221
	v_cvt_pk_bf16_f32 v113, v222, v223
	v_cvt_pk_bf16_f32 v114, v224, v225
	v_cvt_pk_bf16_f32 v115, v226, v227
	v_pk_add_f32 v[122:123], v[226:227], v[222:223]
	v_pk_add_f32 v[120:121], v[224:225], v[220:221]
	v_mfma_f32_32x32x16_bf16 v[128:143], v[182:185], v[164:167], v[128:143]
	ds_read_b128 v[176:179], v213 offset:8192
	v_exp_f32_e32 v124, v124
	v_exp_f32_e32 v125, v125
	v_exp_f32_e32 v126, v126
	v_exp_f32_e32 v127, v127
	s_waitcnt lgkmcnt(0)
	v_mfma_f32_32x32x16_bf16 v[144:159], v[186:189], v[168:171], v[144:159]
	v_add_f32_e64 v122, v230, v122
	v_add_f32_e64 v123, v231, v123
	v_add_f32_e64 v120, v228, v120
	v_add_f32_e64 v121, v229, v121
	v_exp_f32_e32 v182, v96
	v_exp_f32_e32 v183, v97
	v_exp_f32_e32 v184, v98
	v_exp_f32_e32 v185, v99
	v_cvt_pk_bf16_f32 v96, v228, v229
	v_cvt_pk_bf16_f32 v97, v230, v231
	v_cvt_pk_bf16_f32 v98, v124, v125
	v_cvt_pk_bf16_f32 v99, v126, v127
	v_pk_add_f32 v[122:123], v[126:127], v[122:123]
	v_pk_add_f32 v[120:121], v[124:125], v[120:121]
	v_mfma_f32_32x32x16_bf16 v[128:143], v[216:219], v[168:171], v[128:143]
	v_exp_f32_e32 v124, v100
	v_exp_f32_e32 v125, v101
	v_exp_f32_e32 v126, v102
	v_exp_f32_e32 v127, v103
	v_mfma_f32_32x32x16_bf16 v[144:159], v[116:119], v[172:175], v[144:159]
	v_exp_f32_e32 v186, v104
	v_exp_f32_e32 v187, v105
	v_exp_f32_e32 v188, v106
	v_exp_f32_e32 v189, v107
	v_pk_add_f32 v[106:107], v[184:185], v[122:123]
	v_pk_add_f32 v[104:105], v[182:183], v[120:121]
	v_cvt_pk_bf16_f32 v100, v182, v183
	v_cvt_pk_bf16_f32 v101, v184, v185
	v_cvt_pk_bf16_f32 v102, v124, v125
	v_cvt_pk_bf16_f32 v103, v126, v127
	v_pk_add_f32 v[118:119], v[126:127], v[106:107]
	v_pk_add_f32 v[116:117], v[124:125], v[104:105]
	v_mfma_f32_32x32x16_bf16 v[128:143], v[176:179], v[172:175], v[128:143]
	v_exp_f32_e32 v120, v108
	v_exp_f32_e32 v121, v109
	v_exp_f32_e32 v122, v110
	v_exp_f32_e32 v123, v111
	v_pk_add_f32 v[110:111], v[188:189], v[118:119]
	v_pk_add_f32 v[108:109], v[186:187], v[116:117]
	v_cvt_pk_bf16_f32 v104, v186, v187
	v_cvt_pk_bf16_f32 v105, v188, v189
	v_cvt_pk_bf16_f32 v106, v120, v121
	v_cvt_pk_bf16_f32 v107, v122, v123
	v_pk_add_f32 v[178:179], v[122:123], v[110:111]
	v_pk_add_f32 v[176:177], v[120:121], v[108:109]
	s_waitcnt vmcnt(4) lgkmcnt(0)
	s_barrier
	s_add_u32 s70, s98, 0x18000
	s_addc_u32 s71, s99, 0
	s_add_i32 s68, s68, s57
	s_mov_b32 m0, s68
	s_nop 0
	global_load_lds_dwordx4 v198, s[70:71]
	s_add_i32 m0, s68, 0x400
	s_nop 0
	global_load_lds_dwordx4 v194, s[70:71]
	s_add_u32 s2, s100, 0x80
	s_addc_u32 s3, s101, 0
	s_add_i32 s49, s58, s49
	s_add_i32 m0, s49, 0xc000
	s_nop 0
	global_load_lds_dwordx4 v196, s[2:3]
	s_add_i32 m0, s49, 0xc400
	s_nop 0
	global_load_lds_dwordx4 v192, s[2:3]
	s_add_i32 s2, s46, 0xffff4000
	s_add_i32 s3, s48, 1
	s_cmp_lg_u32 s48, 2
	s_cselect_b32 s48, s3, 0
	s_and_b32 s2, s2, 0xc000
	s_add_i32 s2, s2, 0
	s_lshl_b32 s3, s48, 14
	v_add_u32_e32 v124, s2, v206
	ds_read_b128 v[108:111], v124 offset:49152
	ds_read_b128 v[116:119], v124 offset:53248
	ds_read_b128 v[120:123], v124 offset:57344
	ds_read_b128 v[124:127], v124 offset:61440
	s_waitcnt lgkmcnt(0)
	v_mfma_f32_32x32x16_bf16 v[80:95], v[108:111], v[112:115], v[80:95]
	v_xad_u32 v182, v206, 32, s2
	ds_read_b128 v[108:111], v182 offset:49152
	s_add_i32 s3, s3, 0
	v_mfma_f32_32x32x16_bf16 v[64:79], v[116:119], v[112:115], v[64:79]
	ds_read_b128 v[116:119], v182 offset:53248
	v_mfma_f32_32x32x16_bf16 v[16:31], v[120:123], v[112:115], v[16:31]
	ds_read_b128 v[120:123], v182 offset:57344
	v_mfma_f32_32x32x16_bf16 v[0:15], v[124:127], v[112:115], v[0:15]
	ds_read_b128 v[112:115], v182 offset:61440
	s_waitcnt lgkmcnt(0)
	v_mfma_f32_32x32x16_bf16 v[80:95], v[108:111], v[96:99], v[80:95]
	v_xad_u32 v124, v206, 64, s2
	ds_read_b128 v[108:111], v124 offset:49152
	v_mfma_f32_32x32x16_bf16 v[64:79], v[116:119], v[96:99], v[64:79]
	ds_read_b128 v[116:119], v124 offset:53248
	v_mfma_f32_32x32x16_bf16 v[16:31], v[120:123], v[96:99], v[16:31]
	ds_read_b128 v[120:123], v124 offset:57344
	v_mfma_f32_32x32x16_bf16 v[0:15], v[112:115], v[96:99], v[0:15]
	ds_read_b128 v[96:99], v124 offset:61440
	s_waitcnt lgkmcnt(0)
	v_mfma_f32_32x32x16_bf16 v[80:95], v[108:111], v[100:103], v[80:95]
	v_add_u32_e32 v124, s2, v209
	ds_read_b128 v[108:111], v124 offset:49152
	v_mfma_f32_32x32x16_bf16 v[64:79], v[116:119], v[100:103], v[64:79]
	ds_read_b128 v[112:115], v124 offset:53248
	v_mfma_f32_32x32x16_bf16 v[16:31], v[120:123], v[100:103], v[16:31]
	ds_read_b128 v[116:119], v124 offset:57344
	v_mfma_f32_32x32x16_bf16 v[0:15], v[96:99], v[100:103], v[0:15]
	ds_read_b128 v[120:123], v124 offset:61440
	s_waitcnt lgkmcnt(0)
	v_mfma_f32_32x32x16_bf16 v[80:95], v[108:111], v[104:107], v[80:95]
	ds_read_b128 v[96:99], v205 offset:16384
	v_mfma_f32_32x32x16_bf16 v[64:79], v[112:115], v[104:107], v[64:79]
	ds_read_b128 v[100:103], v205 offset:24576
	v_mfma_f32_32x32x16_bf16 v[16:31], v[116:119], v[104:107], v[16:31]
	ds_read_b128 v[182:185], v211 offset:16384
	v_mfma_f32_32x32x16_bf16 v[0:15], v[120:123], v[104:107], v[0:15]
	ds_read_b128 v[186:189], v211 offset:24576
	s_waitcnt lgkmcnt(0)
	v_mfma_f32_32x32x16_bf16 v[112:127], v[96:99], v[160:163], 0
	ds_read_b128 v[216:219], v212 offset:16384
	v_exp_f32_e32 v224, v144
	v_exp_f32_e32 v225, v145
	v_exp_f32_e32 v226, v146
	v_exp_f32_e32 v227, v147
	ds_read_b128 v[220:223], v212 offset:24576
	v_mfma_f32_32x32x16_bf16 v[96:111], v[100:103], v[160:163], 0
	v_exp_f32_e32 v228, v148
	v_exp_f32_e32 v229, v149
	v_exp_f32_e32 v230, v150
	v_exp_f32_e32 v231, v151
	v_mfma_f32_32x32x16_bf16 v[112:127], v[182:185], v[164:167], v[112:127]
	ds_read_b128 v[148:151], v213 offset:16384
	v_exp_f32_e32 v232, v152
	v_exp_f32_e32 v233, v153
	v_exp_f32_e32 v234, v154
	v_exp_f32_e32 v235, v155
	v_cvt_pk_bf16_f32 v144, v224, v225
	v_cvt_pk_bf16_f32 v145, v226, v227
	v_cvt_pk_bf16_f32 v146, v228, v229
	v_cvt_pk_bf16_f32 v147, v230, v231
	v_pk_add_f32 v[154:155], v[230:231], v[226:227]
	v_pk_add_f32 v[152:153], v[228:229], v[224:225]
	v_mfma_f32_32x32x16_bf16 v[96:111], v[186:189], v[164:167], v[96:111]
	ds_read_b128 v[182:185], v213 offset:24576
	v_exp_f32_e32 v156, v156
	v_exp_f32_e32 v157, v157
	v_exp_f32_e32 v158, v158
	v_exp_f32_e32 v159, v159
	s_waitcnt lgkmcnt(0)
	v_mfma_f32_32x32x16_bf16 v[112:127], v[216:219], v[168:171], v[112:127]
	v_add_f32_e64 v154, v234, v154
	v_add_f32_e64 v155, v235, v155
	v_add_f32_e64 v152, v232, v152
	v_add_f32_e64 v153, v233, v153
	v_exp_f32_e32 v186, v128
	v_exp_f32_e32 v187, v129
	v_exp_f32_e32 v188, v130
	v_exp_f32_e32 v189, v131
	v_cvt_pk_bf16_f32 v128, v232, v233
	v_cvt_pk_bf16_f32 v129, v234, v235
	v_cvt_pk_bf16_f32 v130, v156, v157
	v_cvt_pk_bf16_f32 v131, v158, v159
	v_pk_add_f32 v[154:155], v[158:159], v[154:155]
	v_pk_add_f32 v[152:153], v[156:157], v[152:153]
	v_mfma_f32_32x32x16_bf16 v[96:111], v[220:223], v[168:171], v[96:111]
	v_exp_f32_e32 v156, v132
	v_exp_f32_e32 v157, v133
	v_exp_f32_e32 v158, v134
	v_exp_f32_e32 v159, v135
	v_mfma_f32_32x32x16_bf16 v[112:127], v[148:151], v[172:175], v[112:127]
	v_exp_f32_e32 v216, v136
	v_exp_f32_e32 v217, v137
	v_exp_f32_e32 v218, v138
	v_exp_f32_e32 v219, v139
	v_pk_add_f32 v[138:139], v[188:189], v[154:155]
	v_pk_add_f32 v[136:137], v[186:187], v[152:153]
	v_cvt_pk_bf16_f32 v132, v186, v187
	v_cvt_pk_bf16_f32 v133, v188, v189
	v_cvt_pk_bf16_f32 v134, v156, v157
	v_cvt_pk_bf16_f32 v135, v158, v159
	v_pk_add_f32 v[150:151], v[158:159], v[138:139]
	v_pk_add_f32 v[148:149], v[156:157], v[136:137]
	v_mfma_f32_32x32x16_bf16 v[96:111], v[182:185], v[172:175], v[96:111]
	v_exp_f32_e32 v152, v140
	v_exp_f32_e32 v153, v141
	v_exp_f32_e32 v154, v142
	v_exp_f32_e32 v155, v143
	v_pk_add_f32 v[142:143], v[218:219], v[150:151]
	v_pk_add_f32 v[140:141], v[216:217], v[148:149]
	v_cvt_pk_bf16_f32 v136, v216, v217
	v_cvt_pk_bf16_f32 v137, v218, v219
	v_cvt_pk_bf16_f32 v138, v152, v153
	v_cvt_pk_bf16_f32 v139, v154, v155
	v_pk_add_f32 v[142:143], v[154:155], v[142:143]
	v_pk_add_f32 v[140:141], v[152:153], v[140:141]
	s_waitcnt vmcnt(4) lgkmcnt(0)
	v_add_f32_e32 v148, v176, v177
	v_add_f32_e32 v149, v178, v179
	v_add_f32_e32 v148, v148, v149
	v_add_f32_e32 v140, v140, v141
	v_add_f32_e32 v141, v142, v143
	s_barrier
	v_add_f32_e32 v148, v180, v148
	v_add_f32_e32 v140, v140, v141
	v_add_f32_e32 v180, v148, v140
	s_add_i32 s47, s47, 2
	s_addk_i32 s41, 0x80
	s_add_i32 s46, s46, 0x8000
	s_add_u32 s98, s98, 0x30000
	s_addc_u32 s99, s99, 0
	s_add_u32 s100, s100, 0x100
	s_addc_u32 s101, s101, 0
	s_lshl_b32 s49, s48, 14
	s_add_i32 s49, s58, s49
	s_mov_b32 m0, s49
	s_nop 0
	global_load_lds_dwordx4 v198, s[98:99]
	s_add_i32 m0, s49, 0x400
	s_nop 0
	global_load_lds_dwordx4 v194, s[98:99]
	s_add_i32 s49, s46, 0xffffc000
	s_and_b32 s49, s49, 0xc000
	s_add_i32 s49, s58, s49
	s_add_i32 m0, s49, 0xc000
	s_nop 0
	global_load_lds_dwordx4 v196, s[100:101]
	s_add_i32 m0, s49, 0xc400
	s_add_i32 s44, s48, 1
	global_load_lds_dwordx4 v192, s[100:101]
	s_cmp_lg_u32 s48, 2
	s_cselect_b32 s48, s44, 0
	s_lshl_b32 s44, s48, 14
	s_and_b32 s49, s46, 0xc000
	s_add_i32 s68, s44, 0
	s_add_i32 s44, s49, 0
	v_add_u32_e32 v156, s44, v206
	ds_read_b128 v[140:143], v156 offset:49152
	ds_read_b128 v[148:151], v156 offset:53248
	ds_read_b128 v[152:155], v156 offset:57344
	ds_read_b128 v[156:159], v156 offset:61440
	s_waitcnt lgkmcnt(0)
	v_mfma_f32_32x32x16_bf16 v[80:95], v[140:143], v[144:147], v[80:95]
	v_xad_u32 v177, v206, 32, s44
	ds_read_b128 v[140:143], v177 offset:49152
	v_mfma_f32_32x32x16_bf16 v[64:79], v[148:151], v[144:147], v[64:79]
	ds_read_b128 v[148:151], v177 offset:53248
	v_mfma_f32_32x32x16_bf16 v[16:31], v[152:155], v[144:147], v[16:31]
	ds_read_b128 v[152:155], v177 offset:57344
	v_mfma_f32_32x32x16_bf16 v[0:15], v[156:159], v[144:147], v[0:15]
	ds_read_b128 v[144:147], v177 offset:61440
	s_waitcnt lgkmcnt(0)
	v_mfma_f32_32x32x16_bf16 v[80:95], v[140:143], v[128:131], v[80:95]
	v_xad_u32 v156, v206, 64, s44
	ds_read_b128 v[140:143], v156 offset:49152
	v_mfma_f32_32x32x16_bf16 v[64:79], v[148:151], v[128:131], v[64:79]
	ds_read_b128 v[148:151], v156 offset:53248
	v_mfma_f32_32x32x16_bf16 v[16:31], v[152:155], v[128:131], v[16:31]
	ds_read_b128 v[152:155], v156 offset:57344
	v_mfma_f32_32x32x16_bf16 v[0:15], v[144:147], v[128:131], v[0:15]
	ds_read_b128 v[128:131], v156 offset:61440
	s_waitcnt lgkmcnt(0)
	v_mfma_f32_32x32x16_bf16 v[80:95], v[140:143], v[132:135], v[80:95]
	v_add_u32_e32 v156, s44, v209
	ds_read_b128 v[140:143], v156 offset:49152
	v_mfma_f32_32x32x16_bf16 v[64:79], v[148:151], v[132:135], v[64:79]
	ds_read_b128 v[144:147], v156 offset:53248
	v_mfma_f32_32x32x16_bf16 v[16:31], v[152:155], v[132:135], v[16:31]
	ds_read_b128 v[148:151], v156 offset:57344
	v_mfma_f32_32x32x16_bf16 v[0:15], v[128:131], v[132:135], v[0:15]
	ds_read_b128 v[128:131], v156 offset:61440
	s_waitcnt lgkmcnt(0)
	v_mfma_f32_32x32x16_bf16 v[80:95], v[140:143], v[136:139], v[80:95]
	ds_read_b128 v[132:135], v205 offset:32768
	v_mfma_f32_32x32x16_bf16 v[64:79], v[144:147], v[136:139], v[64:79]
	ds_read_b128 v[140:143], v205 offset:40960
	v_mfma_f32_32x32x16_bf16 v[16:31], v[148:151], v[136:139], v[16:31]
	ds_read_b128 v[176:179], v211 offset:32768
	v_mfma_f32_32x32x16_bf16 v[0:15], v[128:131], v[136:139], v[0:15]
	ds_read_b128 v[182:185], v211 offset:40960
	s_waitcnt lgkmcnt(0)
	v_mfma_f32_32x32x16_bf16 v[144:159], v[132:135], v[160:163], 0
	ds_read_b128 v[186:189], v212 offset:32768
	v_exp_f32_e32 v220, v112
	v_exp_f32_e32 v221, v113
	v_exp_f32_e32 v222, v114
	v_exp_f32_e32 v223, v115
	v_mfma_f32_32x32x16_bf16 v[128:143], v[140:143], v[160:163], 0
	ds_read_b128 v[216:219], v212 offset:40960
	v_exp_f32_e32 v224, v116
	v_exp_f32_e32 v225, v117
	v_exp_f32_e32 v226, v118
	v_exp_f32_e32 v227, v119
	v_mfma_f32_32x32x16_bf16 v[144:159], v[176:179], v[164:167], v[144:159]
	ds_read_b128 v[116:119], v213 offset:32768
	v_exp_f32_e32 v228, v120
	v_exp_f32_e32 v229, v121
	v_exp_f32_e32 v230, v122
	v_exp_f32_e32 v231, v123
	v_cvt_pk_bf16_f32 v112, v220, v221
	v_cvt_pk_bf16_f32 v113, v222, v223
	v_cvt_pk_bf16_f32 v114, v224, v225
	v_cvt_pk_bf16_f32 v115, v226, v227
	v_pk_add_f32 v[122:123], v[226:227], v[222:223]
	v_pk_add_f32 v[120:121], v[224:225], v[220:221]
	v_mfma_f32_32x32x16_bf16 v[128:143], v[182:185], v[164:167], v[128:143]
	ds_read_b128 v[176:179], v213 offset:40960
	v_exp_f32_e32 v124, v124
	v_exp_f32_e32 v125, v125
	v_exp_f32_e32 v126, v126
	v_exp_f32_e32 v127, v127
	s_waitcnt lgkmcnt(0)
	v_mfma_f32_32x32x16_bf16 v[144:159], v[186:189], v[168:171], v[144:159]
	v_add_f32_e64 v122, v230, v122
	v_add_f32_e64 v123, v231, v123
	v_add_f32_e64 v120, v228, v120
	v_add_f32_e64 v121, v229, v121
	v_exp_f32_e32 v182, v96
	v_exp_f32_e32 v183, v97
	v_exp_f32_e32 v184, v98
	v_exp_f32_e32 v185, v99
	v_cvt_pk_bf16_f32 v96, v228, v229
	v_cvt_pk_bf16_f32 v97, v230, v231
	v_cvt_pk_bf16_f32 v98, v124, v125
	v_cvt_pk_bf16_f32 v99, v126, v127
	v_pk_add_f32 v[122:123], v[126:127], v[122:123]
	v_pk_add_f32 v[120:121], v[124:125], v[120:121]
	v_mfma_f32_32x32x16_bf16 v[128:143], v[216:219], v[168:171], v[128:143]
	v_exp_f32_e32 v124, v100
	v_exp_f32_e32 v125, v101
	v_exp_f32_e32 v126, v102
	v_exp_f32_e32 v127, v103
	v_mfma_f32_32x32x16_bf16 v[144:159], v[116:119], v[172:175], v[144:159]
	v_exp_f32_e32 v186, v104
	v_exp_f32_e32 v187, v105
	v_exp_f32_e32 v188, v106
	v_exp_f32_e32 v189, v107
	v_pk_add_f32 v[106:107], v[184:185], v[122:123]
	v_pk_add_f32 v[104:105], v[182:183], v[120:121]
	v_cvt_pk_bf16_f32 v100, v182, v183
	v_cvt_pk_bf16_f32 v101, v184, v185
	v_cvt_pk_bf16_f32 v102, v124, v125
	v_cvt_pk_bf16_f32 v103, v126, v127
	v_pk_add_f32 v[118:119], v[126:127], v[106:107]
	v_pk_add_f32 v[116:117], v[124:125], v[104:105]
	v_mfma_f32_32x32x16_bf16 v[128:143], v[176:179], v[172:175], v[128:143]
	v_exp_f32_e32 v120, v108
	v_exp_f32_e32 v121, v109
	v_exp_f32_e32 v122, v110
	v_exp_f32_e32 v123, v111
	v_pk_add_f32 v[110:111], v[188:189], v[118:119]
	v_pk_add_f32 v[108:109], v[186:187], v[116:117]
	v_cvt_pk_bf16_f32 v104, v186, v187
	v_cvt_pk_bf16_f32 v105, v188, v189
	v_cvt_pk_bf16_f32 v106, v120, v121
	v_cvt_pk_bf16_f32 v107, v122, v123
	v_pk_add_f32 v[178:179], v[122:123], v[110:111]
	v_pk_add_f32 v[176:177], v[120:121], v[108:109]
	s_waitcnt vmcnt(4) lgkmcnt(0)
	s_barrier
	s_add_u32 s70, s98, 0x18000
	s_addc_u32 s71, s99, 0
	s_add_i32 s68, s68, s57
	s_mov_b32 m0, s68
	s_nop 0
	global_load_lds_dwordx4 v198, s[70:71]
	s_add_i32 m0, s68, 0x400
	s_nop 0
	global_load_lds_dwordx4 v194, s[70:71]
	s_add_u32 s2, s100, 0x80
	s_addc_u32 s3, s101, 0
	s_add_i32 s49, s58, s49
	s_add_i32 m0, s49, 0xc000
	s_nop 0
	global_load_lds_dwordx4 v196, s[2:3]
	s_add_i32 m0, s49, 0xc400
	s_nop 0
	global_load_lds_dwordx4 v192, s[2:3]
	s_add_i32 s2, s46, 0xffff4000
	s_add_i32 s3, s48, 1
	s_cmp_lg_u32 s48, 2
	s_cselect_b32 s48, s3, 0
	s_and_b32 s2, s2, 0xc000
	s_add_i32 s2, s2, 0
	s_lshl_b32 s3, s48, 14
	v_add_u32_e32 v124, s2, v206
	ds_read_b128 v[108:111], v124 offset:49152
	ds_read_b128 v[116:119], v124 offset:53248
	ds_read_b128 v[120:123], v124 offset:57344
	ds_read_b128 v[124:127], v124 offset:61440
	s_waitcnt lgkmcnt(0)
	v_mfma_f32_32x32x16_bf16 v[80:95], v[108:111], v[112:115], v[80:95]
	v_xad_u32 v182, v206, 32, s2
	ds_read_b128 v[108:111], v182 offset:49152
	s_add_i32 s3, s3, 0
	v_mfma_f32_32x32x16_bf16 v[64:79], v[116:119], v[112:115], v[64:79]
	ds_read_b128 v[116:119], v182 offset:53248
	v_mfma_f32_32x32x16_bf16 v[16:31], v[120:123], v[112:115], v[16:31]
	ds_read_b128 v[120:123], v182 offset:57344
	v_mfma_f32_32x32x16_bf16 v[0:15], v[124:127], v[112:115], v[0:15]
	ds_read_b128 v[112:115], v182 offset:61440
	s_waitcnt lgkmcnt(0)
	v_mfma_f32_32x32x16_bf16 v[80:95], v[108:111], v[96:99], v[80:95]
	v_xad_u32 v124, v206, 64, s2
	ds_read_b128 v[108:111], v124 offset:49152
	v_mfma_f32_32x32x16_bf16 v[64:79], v[116:119], v[96:99], v[64:79]
	ds_read_b128 v[116:119], v124 offset:53248
	v_mfma_f32_32x32x16_bf16 v[16:31], v[120:123], v[96:99], v[16:31]
	ds_read_b128 v[120:123], v124 offset:57344
	v_mfma_f32_32x32x16_bf16 v[0:15], v[112:115], v[96:99], v[0:15]
	ds_read_b128 v[96:99], v124 offset:61440
	s_waitcnt lgkmcnt(0)
	v_mfma_f32_32x32x16_bf16 v[80:95], v[108:111], v[100:103], v[80:95]
	v_add_u32_e32 v124, s2, v209
	ds_read_b128 v[108:111], v124 offset:49152
	v_mfma_f32_32x32x16_bf16 v[64:79], v[116:119], v[100:103], v[64:79]
	ds_read_b128 v[112:115], v124 offset:53248
	v_mfma_f32_32x32x16_bf16 v[16:31], v[120:123], v[100:103], v[16:31]
	ds_read_b128 v[116:119], v124 offset:57344
	v_mfma_f32_32x32x16_bf16 v[0:15], v[96:99], v[100:103], v[0:15]
	ds_read_b128 v[120:123], v124 offset:61440
	s_waitcnt lgkmcnt(0)
	v_mfma_f32_32x32x16_bf16 v[80:95], v[108:111], v[104:107], v[80:95]
	ds_read_b128 v[96:99], v205
	v_mfma_f32_32x32x16_bf16 v[64:79], v[112:115], v[104:107], v[64:79]
	ds_read_b128 v[100:103], v205 offset:8192
	v_mfma_f32_32x32x16_bf16 v[16:31], v[116:119], v[104:107], v[16:31]
	ds_read_b128 v[182:185], v211
	v_mfma_f32_32x32x16_bf16 v[0:15], v[120:123], v[104:107], v[0:15]
	ds_read_b128 v[186:189], v211 offset:8192
	s_waitcnt lgkmcnt(0)
	v_mfma_f32_32x32x16_bf16 v[112:127], v[96:99], v[160:163], 0
	ds_read_b128 v[216:219], v212
	v_exp_f32_e32 v224, v144
	v_exp_f32_e32 v225, v145
	v_exp_f32_e32 v226, v146
	v_exp_f32_e32 v227, v147
	ds_read_b128 v[220:223], v212 offset:8192
	v_mfma_f32_32x32x16_bf16 v[96:111], v[100:103], v[160:163], 0
	v_exp_f32_e32 v228, v148
	v_exp_f32_e32 v229, v149
	v_exp_f32_e32 v230, v150
	v_exp_f32_e32 v231, v151
	v_mfma_f32_32x32x16_bf16 v[112:127], v[182:185], v[164:167], v[112:127]
	ds_read_b128 v[148:151], v213
	v_exp_f32_e32 v232, v152
	v_exp_f32_e32 v233, v153
	v_exp_f32_e32 v234, v154
	v_exp_f32_e32 v235, v155
	v_cvt_pk_bf16_f32 v144, v224, v225
	v_cvt_pk_bf16_f32 v145, v226, v227
	v_cvt_pk_bf16_f32 v146, v228, v229
	v_cvt_pk_bf16_f32 v147, v230, v231
	v_pk_add_f32 v[154:155], v[230:231], v[226:227]
	v_pk_add_f32 v[152:153], v[228:229], v[224:225]
	v_mfma_f32_32x32x16_bf16 v[96:111], v[186:189], v[164:167], v[96:111]
	ds_read_b128 v[182:185], v213 offset:8192
	v_exp_f32_e32 v156, v156
	v_exp_f32_e32 v157, v157
	v_exp_f32_e32 v158, v158
	v_exp_f32_e32 v159, v159
	s_waitcnt lgkmcnt(0)
	v_mfma_f32_32x32x16_bf16 v[112:127], v[216:219], v[168:171], v[112:127]
	v_add_f32_e64 v154, v234, v154
	v_add_f32_e64 v155, v235, v155
	v_add_f32_e64 v152, v232, v152
	v_add_f32_e64 v153, v233, v153
	v_exp_f32_e32 v186, v128
	v_exp_f32_e32 v187, v129
	v_exp_f32_e32 v188, v130
	v_exp_f32_e32 v189, v131
	v_cvt_pk_bf16_f32 v128, v232, v233
	v_cvt_pk_bf16_f32 v129, v234, v235
	v_cvt_pk_bf16_f32 v130, v156, v157
	v_cvt_pk_bf16_f32 v131, v158, v159
	v_pk_add_f32 v[154:155], v[158:159], v[154:155]
	v_pk_add_f32 v[152:153], v[156:157], v[152:153]
	v_mfma_f32_32x32x16_bf16 v[96:111], v[220:223], v[168:171], v[96:111]
	v_exp_f32_e32 v156, v132
	v_exp_f32_e32 v157, v133
	v_exp_f32_e32 v158, v134
	v_exp_f32_e32 v159, v135
	v_mfma_f32_32x32x16_bf16 v[112:127], v[148:151], v[172:175], v[112:127]
	v_exp_f32_e32 v216, v136
	v_exp_f32_e32 v217, v137
	v_exp_f32_e32 v218, v138
	v_exp_f32_e32 v219, v139
	v_pk_add_f32 v[138:139], v[188:189], v[154:155]
	v_pk_add_f32 v[136:137], v[186:187], v[152:153]
	v_cvt_pk_bf16_f32 v132, v186, v187
	v_cvt_pk_bf16_f32 v133, v188, v189
	v_cvt_pk_bf16_f32 v134, v156, v157
	v_cvt_pk_bf16_f32 v135, v158, v159
	v_pk_add_f32 v[150:151], v[158:159], v[138:139]
	v_pk_add_f32 v[148:149], v[156:157], v[136:137]
	v_mfma_f32_32x32x16_bf16 v[96:111], v[182:185], v[172:175], v[96:111]
	v_exp_f32_e32 v152, v140
	v_exp_f32_e32 v153, v141
	v_exp_f32_e32 v154, v142
	v_exp_f32_e32 v155, v143
	v_pk_add_f32 v[142:143], v[218:219], v[150:151]
	v_pk_add_f32 v[140:141], v[216:217], v[148:149]
	v_cvt_pk_bf16_f32 v136, v216, v217
	v_cvt_pk_bf16_f32 v137, v218, v219
	v_cvt_pk_bf16_f32 v138, v152, v153
	v_cvt_pk_bf16_f32 v139, v154, v155
	v_pk_add_f32 v[142:143], v[154:155], v[142:143]
	v_pk_add_f32 v[140:141], v[152:153], v[140:141]
	s_waitcnt vmcnt(4) lgkmcnt(0)
	v_add_f32_e32 v148, v176, v177
	v_add_f32_e32 v149, v178, v179
	v_add_f32_e32 v148, v148, v149
	v_add_f32_e32 v140, v140, v141
	v_add_f32_e32 v141, v142, v143
	s_barrier
	v_add_f32_e32 v148, v180, v148
	v_add_f32_e32 v140, v140, v141
	v_add_f32_e32 v180, v148, v140
	s_add_i32 s47, s47, 2
	s_addk_i32 s41, 0x80
	s_add_i32 s46, s46, 0x8000
	s_add_u32 s98, s98, 0x30000
	s_addc_u32 s99, s99, 0
	s_add_u32 s100, s100, 0x100
	s_addc_u32 s101, s101, 0
	s_cmp_lt_u32 s47, 56
	s_cbranch_scc1 .Lst1_u3
	s_cmp_lt_u32 s47, 60
	s_cbranch_scc1 .Lst1_single
